# speedup vs baseline: 1.0130x; 1.0130x over previous
; __device__ __forceinline__ void dil_wave_item(const bf16* __restrict__ qkv, bf16* __restrict__ odil, float* __restrict__ lse,
;                               int pat, int g  , int head, char* wl  , const int W) {
;     ...
;   const int dil = (pat == 0) ? 1 : (pat == 1 ? 4 : 16);
;   int seq0, slen, gl;
;   if (g < 256) { seq0 = 0; slen = 8192; gl = g; } else if (g < 512) { seq0 = 8192; slen = 8192; gl = g - 256; } else { seq0 = 16384; slen = 16384; gl = g - 512; }
;   const int L = slen / dil, tpr = L / 32, res = gl / tpr, i0 = (gl % tpr) * 32;
; __device__ __forceinline__ void attention_phase(const Params& p, int layer, const int W) {
;     ...
;   for (int it = blockIdx.x; it < 3 * 1024; it += gridDim.x) {
;     dil_wave_item(qkv, odil, lse, it / 1024, it % 1024, wid, lds + wid * 4096, W);
.LBB0_83:
	s_and_b32 s98, s70, 0xffffff00
	s_and_b32 s99, s70, 7
	s_lshl_b32 s99, s99, 5
	s_or_b32 s98, s98, s99
	s_bfe_u32 s99, s70, 0x50003
	s_or_b32 s98, s98, s99
	s_ashr_i32 s4, s98, 31
	s_lshr_b32 s4, s4, 22
	s_add_i32 s4, s98, s4
	s_ashr_i32 s10, s4, 10
	s_and_b32 s4, s4, 0xfffffc00
	s_sub_i32 s6, s98, s4
	s_cmpk_lt_i32 s6, 0x100
	v_mbcnt_lo_u32_b32 v92, -1, 0
	v_mbcnt_hi_u32_b32 v92, -1, v92
	s_cbranch_scc1 .LBB0_89
	s_lshl_b32 s4, s10, 10
	s_sub_i32 s7, s98, s4
	s_cmpk_gt_u32 s6, 0x1ff
	s_mov_b64 s[4:5], -1
	s_cbranch_scc0 .LBB0_86
	s_add_i32 s6, s7, 0xfffffe00
	s_mov_b64 s[4:5], 0

; #define otid() (W * 64 + olane())
; __device__ __forceinline__ void dil_wave_item(const bf16* __restrict__ qkv, bf16* __restrict__ odil, float* __restrict__ lse,
;                               int pat, int g  , int head, char* wl  , const int W) {
;   const int lane = otid() & 63, r32 = lane & 31, hi = lane >> 5;
;   const int dil = (pat == 0) ? 1 : (pat == 1 ? 4 : 16);
;   int seq0, slen, gl;
;   if (g < 256) { seq0 = 0; slen = 8192; gl = g; } else if (g < 512) { seq0 = 8192; slen = 8192; gl = g - 256; } else { seq0 = 16384; slen = 16384; gl = g - 512; }
;   const int L = slen / dil, tpr = L / 32, res = gl / tpr, i0 = (gl % tpr) * 32;
;   const int tbase = seq0 + res;
;   bf16x8 qr[4];
;   { const bf16* qp = qkv + (size_t)(tbase + (i0 + r32) * dil) * LDQ + 1536 + head * 64 + hi * 8;
; #pragma unroll
;     for (int d0 = 0; d0 < 4; ++d0) qr[d0] = *reinterpret_cast<const bf16x8*>(qp + d0 * 16); }
;   f32x16 sc[5];
; #pragma unroll
;   for (int kb = 0; kb < 5; ++kb) {
;     int kc = i0 - 64 + kb * 32 + r32; kc = min(max(kc, 0), L - 1);
;     const bf16* kp = qkv + (size_t)(tbase + kc * dil) * LDQ + 2048 + head * 64 + hi * 8;
;     f32x16 a = {};
; #pragma unroll
;     for (int d0 = 0; d0 < 4; ++d0) {
;       bf16x8 kf = *reinterpret_cast<const bf16x8*>(kp + d0 * 16);
;       a = __builtin_amdgcn_mfma_f32_32x32x16_bf16(kf, qr[d0], a, 0, 0, 0);
;     }
;     sc[kb] = a;
.LBB0_90:
	s_add_i32 s7, s98, 0x3ff
	s_and_b32 s11, s98, 0xfffffc00
	s_cmpk_eq_i32 s11, 0x400
	s_cselect_b32 s11, 2, 4
	s_cmpk_gt_u32 s7, 0x7fe
	s_cselect_b32 s71, s11, 0
	s_lshr_b32 s7, s5, s71
	s_lshr_b32 s5, s7, 5
	s_sext_i32_i16 s11, s5
	v_cvt_f32_i32_e32 v0, s11
	s_sext_i32_i16 s66, s6
	v_cvt_f32_i32_e32 v1, s66
	s_xor_b32 s11, s66, s11
	v_rcp_iflag_f32_e32 v2, v0
	s_ashr_i32 s11, s11, 30
	s_or_b32 s11, s11, 1
	v_and_b32_e32 v91, 31, v92
	v_mul_f32_e32 v2, v1, v2
	v_trunc_f32_e32 v2, v2
	v_fma_f32 v1, -v2, v0, v1
	v_cvt_i32_f32_e32 v2, v2
	v_cmp_ge_f32_e64 s[66:67], |v1|, |v0|
	s_and_b64 s[66:67], s[66:67], exec
	s_cselect_b32 s11, s11, 0
	v_readfirstlane_b32 s66, v2
	s_add_i32 s11, s66, s11
	s_sext_i32_i16 s66, s11
	s_mul_i32 s11, s11, s5
	s_sub_i32 s5, s6, s11
	s_sext_i32_i16 s5, s5
	s_lshl_b32 s78, s5, 5
	v_or_b32_e32 v134, s78, v91
	v_subrev_u32_e32 v87, 64, v134
	s_add_i32 s6, s7, -1
	v_max_i32_e32 v4, 0, v87
	v_min_u32_e32 v4, s6, v4
	s_add_i32 s79, s4, s66
	v_lshlrev_b32_e32 v4, s71, v4
	v_add_u32_e32 v4, s79, v4
	v_bfe_u32 v90, v92, 5, 1
	v_mad_i64_i32 v[4:5], s[4:5], v4, s62, v[84:85]
	v_lshlrev_b32_e32 v82, 4, v90
	v_lshl_add_u64 v[4:5], v[4:5], 0, s[74:75]
	v_lshl_add_u64 v[20:21], v[4:5], 0, v[82:83]
	v_max_i32_e32 v8, 0xffffffe0, v87
	v_add_co_u32_e32 v4, vcc, s63, v20
	v_add_u32_e32 v8, 32, v8
	s_nop 0
	v_addc_co_u32_e32 v5, vcc, 0, v21, vcc
	v_min_u32_e32 v8, s6, v8
	v_lshlrev_b32_e32 v86, s71, v134
	global_load_dwordx4 v[4:7], v[4:5], off
	v_lshlrev_b32_e32 v8, s71, v8
	v_add_u32_e32 v0, s79, v86
	v_add_u32_e32 v8, s79, v8
	v_mad_i64_i32 v[0:1], s[4:5], v0, s62, v[80:81]
	v_mad_i64_i32 v[8:9], s[4:5], v8, s62, v[84:85]
	v_lshl_add_u64 v[126:127], v[0:1], 0, v[82:83]
	v_lshl_add_u64 v[8:9], v[8:9], 0, s[74:75]
	global_load_dwordx4 v[0:3], v[126:127], off offset:3072
	v_lshl_add_u64 v[22:23], v[8:9], 0, v[82:83]
	v_add_co_u32_e32 v8, vcc, s63, v22
	v_max_i32_e32 v12, 0xffffffc0, v87
	s_nop 0
	v_addc_co_u32_e32 v9, vcc, 0, v23, vcc
	global_load_dwordx4 v[8:11], v[8:9], off
	v_add_u32_e32 v12, 64, v12
	v_min_u32_e32 v12, s6, v12
	s_waitcnt vmcnt(11)
	v_max_i32_e32 v16, 0xffffffa0, v87
	v_lshlrev_b32_e32 v12, s71, v12
	v_add_u32_e32 v16, 0x60, v16
	v_add_u32_e32 v12, s79, v12
	v_min_u32_e32 v16, s6, v16
	v_mad_i64_i32 v[12:13], s[4:5], v12, s62, v[84:85]
	v_lshlrev_b32_e32 v16, s71, v16
	v_lshl_add_u64 v[12:13], v[12:13], 0, s[74:75]
	v_add_u32_e32 v16, s79, v16
	v_lshl_add_u64 v[24:25], v[12:13], 0, v[82:83]
	v_mad_i64_i32 v[16:17], s[4:5], v16, s62, v[84:85]
	v_add_co_u32_e32 v12, vcc, s63, v24
	v_lshl_add_u64 v[16:17], v[16:17], 0, s[74:75]
	s_nop 0
	v_addc_co_u32_e32 v13, vcc, 0, v25, vcc
	v_lshl_add_u64 v[26:27], v[16:17], 0, v[82:83]
	v_add_co_u32_e32 v16, vcc, s63, v26
	global_load_dwordx4 v[12:15], v[12:13], off
	s_nop 0
	v_addc_co_u32_e32 v17, vcc, 0, v27, vcc
	v_lshl_add_u64 v[118:119], v[20:21], 0, s[8:9]
	v_lshl_add_u64 v[128:129], v[22:23], 0, s[8:9]
	global_load_dwordx4 v[16:19], v[16:17], off
	s_nop 0
	global_load_dwordx4 v[94:97], v[118:119], off offset:32
	global_load_dwordx4 v[98:101], v[126:127], off offset:3104
	global_load_dwordx4 v[102:105], v[118:119], off offset:96
	v_lshl_add_u64 v[130:131], v[24:25], 0, s[8:9]
	v_lshl_add_u64 v[132:133], v[26:27], 0, s[8:9]
	v_lshlrev_b32_e32 v90, 2, v90
	v_sub_u32_e32 v93, v90, v91
	s_waitcnt vmcnt(6)
	v_mfma_f32_32x32x16_bf16 v[64:79], v[4:7], v[0:3], 0
	global_load_dwordx4 v[4:7], v[128:129], off offset:32
	global_load_dwordx4 v[106:109], v[128:129], off offset:96
	global_load_dwordx4 v[110:113], v[130:131], off offset:96
	s_waitcnt vmcnt(8)
	v_mfma_f32_32x32x16_bf16 v[48:63], v[8:11], v[0:3], 0
	global_load_dwordx4 v[8:11], v[130:131], off offset:32
	s_waitcnt vmcnt(8)
	v_mfma_f32_32x32x16_bf16 v[32:47], v[12:15], v[0:3], 0
	global_load_dwordx4 v[12:15], v[132:133], off offset:32
	global_load_dwordx4 v[114:117], v[132:133], off offset:96
	s_nop 0
	global_load_dwordx4 v[118:121], v[118:119], off offset:64
	s_nop 0
	global_load_dwordx4 v[122:125], v[126:127], off offset:3136
	s_waitcnt vmcnt(9)
	v_mfma_f32_32x32x16_bf16 v[64:79], v[94:97], v[98:101], v[64:79]
	global_load_dwordx4 v[94:97], v[128:129], off offset:64
	v_mfma_f32_32x32x16_bf16 v[16:31], v[16:19], v[0:3], 0
	s_waitcnt vmcnt(4)
	v_mfma_f32_32x32x16_bf16 v[16:31], v[12:15], v[98:101], v[16:31]
	v_mfma_f32_32x32x16_bf16 v[48:63], v[4:7], v[98:101], v[48:63]
	global_load_dwordx4 v[4:7], v[130:131], off offset:64
	s_nop 0
	global_load_dwordx4 v[126:129], v[126:127], off offset:3168
	v_mfma_f32_32x32x16_bf16 v[32:47], v[8:11], v[98:101], v[32:47]
	global_load_dwordx4 v[8:11], v[132:133], off offset:64
	s_waitcnt vmcnt(3)
	v_mfma_f32_32x32x16_bf16 v[48:63], v[94:97], v[122:125], v[48:63]
	s_waitcnt vmcnt(2)
	v_mfma_f32_32x32x16_bf16 v[32:47], v[4:7], v[122:125], v[32:47]
	v_max_i32_e32 v4, 0xffffff80, v87
	v_add_u32_e32 v4, 0x80, v4
	v_min_u32_e32 v4, s6, v4
	v_lshlrev_b32_e32 v4, s71, v4
	v_add_u32_e32 v4, s79, v4
	v_mad_i64_i32 v[4:5], s[4:5], v4, s62, v[84:85]
	v_lshl_add_u64 v[4:5], v[4:5], 0, s[74:75]
	s_waitcnt vmcnt(0)
	v_mfma_f32_32x32x16_bf16 v[16:31], v[8:11], v[122:125], v[16:31]
	v_lshl_add_u64 v[8:9], v[4:5], 0, v[82:83]
	v_add_co_u32_e32 v4, vcc, s63, v8
	v_and_b32_e32 v87, 63, v92
	s_nop 0
	v_addc_co_u32_e32 v5, vcc, 0, v9, vcc
	global_load_dwordx4 v[4:7], v[4:5], off
	v_mfma_f32_32x32x16_bf16 v[64:79], v[118:121], v[122:125], v[64:79]
	v_cmp_gt_u32_e32 vcc, s64, v93
	v_mfma_f32_32x32x16_bf16 v[48:63], v[106:109], v[126:129], v[48:63]
	v_lshl_add_u64 v[106:107], v[8:9], 0, s[8:9]
	v_mfma_f32_32x32x16_bf16 v[64:79], v[102:105], v[126:129], v[64:79]
	global_load_dwordx4 v[94:97], v[106:107], off offset:32
	global_load_dwordx4 v[102:105], v[106:107], off offset:96
	s_nop 7
	v_mul_f32_e32 v48, 0x3e38aa3b, v48
	global_load_dwordx4 v[106:109], v[106:107], off offset:64
	v_mul_f32_e32 v49, 0x3e38aa3b, v49
	v_mul_f32_e32 v50, 0x3e38aa3b, v50
	v_mul_f32_e32 v51, 0x3e38aa3b, v51
	v_mul_f32_e32 v52, 0x3e38aa3b, v52
	s_waitcnt vmcnt(3)
; __device__ __forceinline__ int crow(int r, int hi) { return (r & 3) + 8 * (r >> 2) + 4 * hi; }
; __device__ __forceinline__ void dil_wave_item(const bf16* __restrict__ qkv, bf16* __restrict__ odil, float* __restrict__ lse,
;                               int pat, int g  , int head, char* wl  , const int W) {
;     ...
;   for (int kb = 0; kb < 5; ++kb) {
;     int kc = i0 - 64 + kb * 32 + r32; kc = min(max(kc, 0), L - 1);
;     const bf16* kp = qkv + (size_t)(tbase + kc * dil) * LDQ + 2048 + head * 64 + hi * 8;
;     f32x16 a = {};
; #pragma unroll
;     for (int d0 = 0; d0 < 4; ++d0) {
;       bf16x8 kf = *reinterpret_cast<const bf16x8*>(kp + d0 * 16);
;       a = __builtin_amdgcn_mfma_f32_32x32x16_bf16(kf, qr[d0], a, 0, 0, 0);
;     }
;     sc[kb] = a;
;   }
;   float mx = -1e30f;
; #pragma unroll
;   for (int kb = 0; kb < 5; ++kb)
; #pragma unroll
;     for (int r = 0; r < 16; ++r) {
;       const int rel = kb * 32 - 64 + crow(r, hi) - r32;
;       const int kc = i0 + r32 + rel;
;       const bool ok = (rel >= -64) && (rel <= 64) && (kc >= 0) && (kc < L);
;       const float s = ok ? sc[kb][r] * AC : -1e30f;
;       sc[kb][r] = s; mx = fmaxf(mx, s);
;     }
;     ...
;     for (int i = 0; i < 4; ++i) {
;       const int key = i * 8 + (lane >> 3);
;       int kc = i0 - 64 + kb * 32 + key; kc = min(max(kc, 0), L - 1);
;       vr[i] = *reinterpret_cast<const bf16x8*>(qkv + (size_t)(tbase + kc * dil) * LDQ + 2560 + head * 64 + (lane & 7) * 8);
	v_mfma_f32_32x32x16_bf16 v[0:15], v[4:7], v[0:3], 0
	v_mul_f32_e32 v64, 0x3e38aa3b, v64
	v_mul_f32_e32 v65, 0x3e38aa3b, v65
	v_mul_f32_e32 v66, 0x3e38aa3b, v66
	v_mul_f32_e32 v67, 0x3e38aa3b, v67
	v_mul_f32_e32 v68, 0x3e38aa3b, v68
	v_mul_f32_e32 v69, 0x3e38aa3b, v69
	v_mul_f32_e32 v70, 0x3e38aa3b, v70
	s_waitcnt vmcnt(2)
	v_mfma_f32_32x32x16_bf16 v[0:15], v[94:97], v[98:101], v[0:15]
	v_add_u32_e32 v94, v134, v93
	v_subrev_u32_e32 v95, 64, v94
	v_cmp_gt_u32_e64 s[4:5], s7, v95
	s_and_b64 vcc, vcc, s[4:5]
	v_subrev_u32_e32 v95, 63, v94
	v_add_u32_e32 v96, 1, v93
	v_cndmask_b32_e32 v64, v89, v64, vcc
	v_cmp_gt_u32_e32 vcc, s64, v96
	v_cmp_gt_u32_e64 s[4:5], s7, v95
	s_waitcnt vmcnt(0)
	v_mfma_f32_32x32x16_bf16 v[0:15], v[106:109], v[122:125], v[0:15]
	v_bfe_u32 v232, v92, 3, 3
	v_and_b32_e32 v233, 7, v92
	v_add_u32_e32 v232, s78, v232
	v_lshlrev_b32_e32 v233, 4, v233
	v_add_u32_e32 v233, s74, v233
	v_add_u32_e32 v233, 0x1400, v233
	v_add_u32_e32 v234, 0xffffffc0, v232
	v_max_i32_e32 v234, 0, v234
	v_min_u32_e32 v234, s6, v234
	v_lshlrev_b32_e32 v234, s71, v234
	v_add_u32_e32 v234, s79, v234
	v_mad_u32_u24 v234, v234, s62, v233
	global_load_dwordx4 v[152:155], v234, s[36:37]
	v_add_u32_e32 v235, 0xffffffc8, v232
	v_max_i32_e32 v235, 0, v235
	v_min_u32_e32 v235, s6, v235
	v_lshlrev_b32_e32 v235, s71, v235
	v_add_u32_e32 v235, s79, v235
	v_mad_u32_u24 v235, v235, s62, v233
	global_load_dwordx4 v[156:159], v235, s[36:37]
	v_add_u32_e32 v234, 0xffffffd0, v232
	v_max_i32_e32 v234, 0, v234
	v_min_u32_e32 v234, s6, v234
	v_lshlrev_b32_e32 v234, s71, v234
	v_add_u32_e32 v234, s79, v234
	v_mad_u32_u24 v234, v234, s62, v233
	global_load_dwordx4 v[160:163], v234, s[36:37]
	v_add_u32_e32 v235, 0xffffffd8, v232
	v_max_i32_e32 v235, 0, v235
	v_min_u32_e32 v235, s6, v235
	v_lshlrev_b32_e32 v235, s71, v235
	v_add_u32_e32 v235, s79, v235
	v_mad_u32_u24 v235, v235, s62, v233
	global_load_dwordx4 v[164:167], v235, s[36:37]
	v_add_u32_e32 v234, 0xffffffe0, v232
	v_max_i32_e32 v234, 0, v234
	v_min_u32_e32 v234, s6, v234
	v_lshlrev_b32_e32 v234, s71, v234
	v_add_u32_e32 v234, s79, v234
	v_mad_u32_u24 v234, v234, s62, v233
	global_load_dwordx4 v[168:171], v234, s[36:37]
	v_add_u32_e32 v235, 0xffffffe8, v232
	v_max_i32_e32 v235, 0, v235
	v_min_u32_e32 v235, s6, v235
	v_lshlrev_b32_e32 v235, s71, v235
	v_add_u32_e32 v235, s79, v235
	v_mad_u32_u24 v235, v235, s62, v233
	global_load_dwordx4 v[172:175], v235, s[36:37]
	v_add_u32_e32 v234, -16, v232
	v_max_i32_e32 v234, 0, v234
	v_min_u32_e32 v234, s6, v234
	v_lshlrev_b32_e32 v234, s71, v234
	v_add_u32_e32 v234, s79, v234
	v_mad_u32_u24 v234, v234, s62, v233
	global_load_dwordx4 v[176:179], v234, s[36:37]
	v_add_u32_e32 v235, -8, v232
	v_max_i32_e32 v235, 0, v235
	v_min_u32_e32 v235, s6, v235
	v_lshlrev_b32_e32 v235, s71, v235
	v_add_u32_e32 v235, s79, v235
	v_mad_u32_u24 v235, v235, s62, v233
	global_load_dwordx4 v[180:183], v235, s[36:37]
	v_add_u32_e32 v234, 0, v232
	v_max_i32_e32 v234, 0, v234
	v_min_u32_e32 v234, s6, v234
	v_lshlrev_b32_e32 v234, s71, v234
	v_add_u32_e32 v234, s79, v234
	v_mad_u32_u24 v234, v234, s62, v233
	global_load_dwordx4 v[184:187], v234, s[36:37]
	v_add_u32_e32 v235, 8, v232
	v_max_i32_e32 v235, 0, v235
	v_min_u32_e32 v235, s6, v235
	v_lshlrev_b32_e32 v235, s71, v235
	v_add_u32_e32 v235, s79, v235
	v_mad_u32_u24 v235, v235, s62, v233
	global_load_dwordx4 v[188:191], v235, s[36:37]
	v_add_u32_e32 v234, 16, v232
	v_max_i32_e32 v234, 0, v234
	v_min_u32_e32 v234, s6, v234
	v_lshlrev_b32_e32 v234, s71, v234
	v_add_u32_e32 v234, s79, v234
	v_mad_u32_u24 v234, v234, s62, v233
	global_load_dwordx4 v[192:195], v234, s[36:37]
	v_add_u32_e32 v235, 24, v232
	v_max_i32_e32 v235, 0, v235
	v_min_u32_e32 v235, s6, v235
	v_lshlrev_b32_e32 v235, s71, v235
	v_add_u32_e32 v235, s79, v235
	v_mad_u32_u24 v235, v235, s62, v233
	global_load_dwordx4 v[196:199], v235, s[36:37]
	v_add_u32_e32 v234, 32, v232
	v_max_i32_e32 v234, 0, v234
	v_min_u32_e32 v234, s6, v234
	v_lshlrev_b32_e32 v234, s71, v234
	v_add_u32_e32 v234, s79, v234
	v_mad_u32_u24 v234, v234, s62, v233
	global_load_dwordx4 v[200:203], v234, s[36:37]
	v_add_u32_e32 v235, 40, v232
	v_max_i32_e32 v235, 0, v235
	v_min_u32_e32 v235, s6, v235
	v_lshlrev_b32_e32 v235, s71, v235
	v_add_u32_e32 v235, s79, v235
	v_mad_u32_u24 v235, v235, s62, v233
	global_load_dwordx4 v[204:207], v235, s[36:37]
	v_add_u32_e32 v234, 48, v232
	v_max_i32_e32 v234, 0, v234
	v_min_u32_e32 v234, s6, v234
	v_lshlrev_b32_e32 v234, s71, v234
	v_add_u32_e32 v234, s79, v234
	v_mad_u32_u24 v234, v234, s62, v233
	global_load_dwordx4 v[208:211], v234, s[36:37]
	v_add_u32_e32 v235, 56, v232
	v_max_i32_e32 v235, 0, v235
	v_min_u32_e32 v235, s6, v235
	v_lshlrev_b32_e32 v235, s71, v235
	v_add_u32_e32 v235, s79, v235
	v_mad_u32_u24 v235, v235, s62, v233
	global_load_dwordx4 v[212:215], v235, s[36:37]
	v_add_u32_e32 v234, 64, v232
	v_max_i32_e32 v234, 0, v234
	v_min_u32_e32 v234, s6, v234
	v_lshlrev_b32_e32 v234, s71, v234
	v_add_u32_e32 v234, s79, v234
	v_mad_u32_u24 v234, v234, s62, v233
	global_load_dwordx4 v[216:219], v234, s[36:37]
	v_add_u32_e32 v235, 0x00000048, v232
	v_max_i32_e32 v235, 0, v235
	v_min_u32_e32 v235, s6, v235
	v_lshlrev_b32_e32 v235, s71, v235
	v_add_u32_e32 v235, s79, v235
	v_mad_u32_u24 v235, v235, s62, v233
	global_load_dwordx4 v[220:223], v235, s[36:37]
	v_add_u32_e32 v234, 0x00000050, v232
	v_max_i32_e32 v234, 0, v234
	v_min_u32_e32 v234, s6, v234
	v_lshlrev_b32_e32 v234, s71, v234
	v_add_u32_e32 v234, s79, v234
	v_mad_u32_u24 v234, v234, s62, v233
	global_load_dwordx4 v[224:227], v234, s[36:37]
	v_add_u32_e32 v235, 0x00000058, v232
	v_max_i32_e32 v235, 0, v235
; __device__ __forceinline__ int crow(int r, int hi) { return (r & 3) + 8 * (r >> 2) + 4 * hi; }
; __device__ __forceinline__ void dil_wave_item(const bf16* __restrict__ qkv, bf16* __restrict__ odil, float* __restrict__ lse,
;                               int pat, int g  , int head, char* wl  , const int W) {
;     ...
;   float mx = -1e30f;
; #pragma unroll
;   for (int kb = 0; kb < 5; ++kb)
; #pragma unroll
;     for (int r = 0; r < 16; ++r) {
;       const int rel = kb * 32 - 64 + crow(r, hi) - r32;
;       const int kc = i0 + r32 + rel;
;       const bool ok = (rel >= -64) && (rel <= 64) && (kc >= 0) && (kc < L);
;       const float s = ok ? sc[kb][r] * AC : -1e30f;
;       sc[kb][r] = s; mx = fmaxf(mx, s);
;     }
	v_min_u32_e32 v235, s6, v235
	v_lshlrev_b32_e32 v235, s71, v235
	v_add_u32_e32 v235, s79, v235
	v_mad_u32_u24 v235, v235, s62, v233
	global_load_dwordx4 v[228:231], v235, s[36:37]
	s_and_b64 vcc, vcc, s[4:5]
	v_subrev_u32_e32 v97, 62, v94
	v_add_u32_e32 v98, 2, v93
	v_cndmask_b32_e32 v65, v89, v65, vcc
	v_cmp_gt_u32_e32 vcc, s64, v98
	v_cmp_gt_u32_e64 s[4:5], s7, v97
	s_and_b64 vcc, vcc, s[4:5]
	v_subrev_u32_e32 v97, 61, v94
	v_add_u32_e32 v99, 3, v93
	v_cndmask_b32_e32 v66, v89, v66, vcc
	v_cmp_gt_u32_e32 vcc, s64, v99
	v_cmp_gt_u32_e64 s[4:5], s7, v97
	s_and_b64 vcc, vcc, s[4:5]
	v_subrev_u32_e32 v97, 56, v94
	v_add_u32_e32 v100, 8, v93
	v_cndmask_b32_e32 v67, v89, v67, vcc
	v_cmp_gt_u32_e32 vcc, s64, v100
	v_cmp_gt_u32_e64 s[4:5], s7, v97
	s_and_b64 vcc, vcc, s[4:5]
	v_subrev_u32_e32 v97, 55, v94
	v_add_u32_e32 v101, 9, v93
	v_cndmask_b32_e32 v68, v89, v68, vcc
	v_cmp_gt_u32_e32 vcc, s64, v101
	v_cmp_gt_u32_e64 s[4:5], s7, v97
	v_mfma_f32_32x32x16_bf16 v[0:15], v[102:105], v[126:129], v[0:15]
	s_and_b64 vcc, vcc, s[4:5]
	v_subrev_u32_e32 v97, 54, v94
	v_add_u32_e32 v102, 10, v93
	v_cndmask_b32_e32 v69, v89, v69, vcc
	v_cmp_gt_u32_e32 vcc, s64, v102
	v_cmp_gt_u32_e64 s[4:5], s7, v97
	s_and_b64 vcc, vcc, s[4:5]
	v_subrev_u32_e32 v97, 53, v94
	v_add_u32_e32 v103, 11, v93
	v_cndmask_b32_e32 v70, v89, v70, vcc
	v_cmp_gt_u32_e32 vcc, s64, v103
	v_cmp_gt_u32_e64 s[4:5], s7, v97
	v_mul_f32_e32 v71, 0x3e38aa3b, v71
	s_and_b64 vcc, vcc, s[4:5]
	v_subrev_u32_e32 v97, 48, v94
	v_add_u32_e32 v104, 16, v93
	v_cndmask_b32_e32 v71, v89, v71, vcc
	v_cmp_gt_u32_e32 vcc, s64, v104
	v_cmp_gt_u32_e64 s[4:5], s7, v97
	v_mul_f32_e32 v72, 0x3e38aa3b, v72
	s_and_b64 vcc, vcc, s[4:5]
	v_subrev_u32_e32 v97, 47, v94
	v_add_u32_e32 v105, 17, v93
	v_cndmask_b32_e32 v72, v89, v72, vcc
	v_cmp_gt_u32_e32 vcc, s64, v105
	v_cmp_gt_u32_e64 s[4:5], s7, v97
	v_mul_f32_e32 v73, 0x3e38aa3b, v73
	s_and_b64 vcc, vcc, s[4:5]
	v_subrev_u32_e32 v97, 46, v94
	v_add_u32_e32 v106, 18, v93
	v_cndmask_b32_e32 v73, v89, v73, vcc
	v_cmp_gt_u32_e32 vcc, s64, v106
	v_cmp_gt_u32_e64 s[4:5], s7, v97
	v_mul_f32_e32 v74, 0x3e38aa3b, v74
	s_and_b64 vcc, vcc, s[4:5]
	v_subrev_u32_e32 v97, 45, v94
	v_add_u32_e32 v107, 19, v93
	v_cndmask_b32_e32 v74, v89, v74, vcc
	v_cmp_gt_u32_e32 vcc, s64, v107
	v_cmp_gt_u32_e64 s[4:5], s7, v97
	v_mul_f32_e32 v75, 0x3e38aa3b, v75
	s_and_b64 vcc, vcc, s[4:5]
	v_subrev_u32_e32 v97, 40, v94
	v_add_u32_e32 v108, 24, v93
	v_cndmask_b32_e32 v75, v89, v75, vcc
	v_cmp_gt_u32_e32 vcc, s64, v108
	v_cmp_gt_u32_e64 s[4:5], s7, v97
	v_mul_f32_e32 v76, 0x3e38aa3b, v76
	s_and_b64 vcc, vcc, s[4:5]
	v_subrev_u32_e32 v97, 39, v94
	v_add_u32_e32 v109, 25, v93
	v_cndmask_b32_e32 v76, v89, v76, vcc
	v_cmp_gt_u32_e32 vcc, s64, v109
	v_cmp_gt_u32_e64 s[4:5], s7, v97
	v_mfma_f32_32x32x16_bf16 v[32:47], v[110:113], v[126:129], v[32:47]
	v_mul_f32_e32 v77, 0x3e38aa3b, v77
	s_and_b64 vcc, vcc, s[4:5]
	v_subrev_u32_e32 v97, 38, v94
	v_add_u32_e32 v110, 26, v93
	v_cndmask_b32_e32 v77, v89, v77, vcc
	v_cmp_gt_u32_e32 vcc, s64, v110
	v_cmp_gt_u32_e64 s[4:5], s7, v97
	v_mul_f32_e32 v78, 0x3e38aa3b, v78
	s_and_b64 vcc, vcc, s[4:5]
	v_subrev_u32_e32 v97, 37, v94
	v_add_u32_e32 v111, 27, v93
	v_cndmask_b32_e32 v78, v89, v78, vcc
	v_cmp_gt_u32_e32 vcc, s64, v111
	v_cmp_gt_u32_e64 s[4:5], s7, v97
	v_mul_f32_e32 v79, 0x3e38aa3b, v79
	s_and_b64 vcc, vcc, s[4:5]
	v_subrev_u32_e32 v97, 32, v94
	v_cndmask_b32_e32 v79, v89, v79, vcc
	v_cmp_gt_u32_e32 vcc, s7, v97
	v_subrev_u32_e32 v97, 31, v94
	v_max3_f32 v95, v64, s65, v65
	v_cndmask_b32_e32 v48, v89, v48, vcc
	v_cmp_gt_u32_e32 vcc, s7, v97
	v_subrev_u32_e32 v97, 30, v94
	v_mul_f32_e32 v53, 0x3e38aa3b, v53
	v_cndmask_b32_e32 v49, v89, v49, vcc
	v_cmp_gt_u32_e32 vcc, s7, v97
	v_subrev_u32_e32 v97, 29, v94
	v_max3_f32 v95, v95, v66, v67
	v_cndmask_b32_e32 v50, v89, v50, vcc
	v_cmp_gt_u32_e32 vcc, s7, v97
	v_subrev_u32_e32 v97, 24, v94
	v_mul_f32_e32 v54, 0x3e38aa3b, v54
	v_cndmask_b32_e32 v51, v89, v51, vcc
	v_cmp_gt_u32_e32 vcc, s7, v97
	v_subrev_u32_e32 v97, 23, v94
	v_max3_f32 v95, v95, v68, v69
	v_cndmask_b32_e32 v52, v89, v52, vcc
	v_cmp_gt_u32_e32 vcc, s7, v97
	v_subrev_u32_e32 v97, 22, v94
	v_mul_f32_e32 v55, 0x3e38aa3b, v55
	v_cndmask_b32_e32 v53, v89, v53, vcc
	v_cmp_gt_u32_e32 vcc, s7, v97
	v_subrev_u32_e32 v97, 21, v94
	v_max3_f32 v95, v95, v70, v71
	v_cndmask_b32_e32 v54, v89, v54, vcc
	v_cmp_gt_u32_e32 vcc, s7, v97
	v_add_u32_e32 v97, -16, v94
	v_mul_f32_e32 v56, 0x3e38aa3b, v56
	v_cndmask_b32_e32 v55, v89, v55, vcc
	v_cmp_gt_u32_e32 vcc, s7, v97
	v_add_u32_e32 v97, -15, v94
	v_max3_f32 v95, v95, v72, v73
	v_cndmask_b32_e32 v56, v89, v56, vcc
	v_mul_f32_e32 v57, 0x3e38aa3b, v57
	v_cmp_gt_u32_e32 vcc, s7, v97
	v_add_u32_e32 v97, -14, v94
	v_max3_f32 v95, v95, v74, v75
	v_cndmask_b32_e32 v57, v89, v57, vcc
	v_mul_f32_e32 v58, 0x3e38aa3b, v58
	v_cmp_gt_u32_e32 vcc, s7, v97
	v_add_u32_e32 v97, -13, v94
	v_max3_f32 v95, v95, v76, v77
	v_cndmask_b32_e32 v58, v89, v58, vcc
	v_mul_f32_e32 v59, 0x3e38aa3b, v59
	v_cmp_gt_u32_e32 vcc, s7, v97
	v_add_u32_e32 v97, -8, v94
	v_max3_f32 v95, v95, v78, v79
	v_cndmask_b32_e32 v59, v89, v59, vcc
	v_mul_f32_e32 v60, 0x3e38aa3b, v60
	v_cmp_gt_u32_e32 vcc, s7, v97
	v_add_u32_e32 v97, -7, v94
	v_max3_f32 v95, v95, v48, v49
	v_cndmask_b32_e32 v60, v89, v60, vcc
	v_mul_f32_e32 v61, 0x3e38aa3b, v61
	v_cmp_gt_u32_e32 vcc, s7, v97
	v_add_u32_e32 v97, -6, v94
	v_max3_f32 v95, v95, v50, v51
	v_cndmask_b32_e32 v61, v89, v61, vcc
	v_mul_f32_e32 v62, 0x3e38aa3b, v62
	v_cmp_gt_u32_e32 vcc, s7, v97
	v_add_u32_e32 v97, -5, v94
	v_max3_f32 v95, v95, v52, v53
	v_cndmask_b32_e32 v62, v89, v62, vcc
	v_mul_f32_e32 v63, 0x3e38aa3b, v63
; __device__ __forceinline__ int crow(int r, int hi) { return (r & 3) + 8 * (r >> 2) + 4 * hi; }
; __device__ __forceinline__ void dil_wave_item(const bf16* __restrict__ qkv, bf16* __restrict__ odil, float* __restrict__ lse,
;                               int pat, int g  , int head, char* wl  , const int W) {
;     ...
;   float mx = -1e30f;
; #pragma unroll
;   for (int kb = 0; kb < 5; ++kb)
; #pragma unroll
;     for (int r = 0; r < 16; ++r) {
;       const int rel = kb * 32 - 64 + crow(r, hi) - r32;
;       const int kc = i0 + r32 + rel;
;       const bool ok = (rel >= -64) && (rel <= 64) && (kc >= 0) && (kc < L);
;       const float s = ok ? sc[kb][r] * AC : -1e30f;
;       sc[kb][r] = s; mx = fmaxf(mx, s);
;     }
	v_cmp_gt_u32_e32 vcc, s7, v97
	v_max3_f32 v95, v95, v54, v55
	v_mul_f32_e32 v32, 0x3e38aa3b, v32
	v_cndmask_b32_e32 v63, v89, v63, vcc
	v_cmp_gt_u32_e32 vcc, s7, v94
	v_add_u32_e32 v96, v134, v96
	v_max3_f32 v95, v95, v56, v57
	v_cndmask_b32_e32 v32, v89, v32, vcc
	v_mul_f32_e32 v33, 0x3e38aa3b, v33
	v_cmp_gt_u32_e32 vcc, s7, v96
	v_add_u32_e32 v96, v134, v98
	v_max3_f32 v95, v95, v58, v59
	v_cndmask_b32_e32 v33, v89, v33, vcc
	v_mul_f32_e32 v34, 0x3e38aa3b, v34
	v_cmp_gt_u32_e32 vcc, s7, v96
	v_max3_f32 v95, v95, v60, v61
	v_max3_f32 v95, v95, v62, v63
	v_cndmask_b32_e32 v96, v89, v34, vcc
	v_add_u32_e32 v34, v134, v99
	v_mul_f32_e32 v35, 0x3e38aa3b, v35
	v_cmp_gt_u32_e32 vcc, s7, v34
	v_max3_f32 v95, v95, v32, v33
	v_mul_f32_e32 v36, 0x3e38aa3b, v36
	v_cndmask_b32_e32 v35, v89, v35, vcc
	v_max3_f32 v34, v95, v96, v35
	v_add_u32_e32 v95, v134, v100
	v_cmp_gt_u32_e32 vcc, s7, v95
	v_add_u32_e32 v95, v134, v101
	v_mul_f32_e32 v37, 0x3e38aa3b, v37
	v_cndmask_b32_e32 v36, v89, v36, vcc
	v_cmp_gt_u32_e32 vcc, s7, v95
	v_add_u32_e32 v95, v134, v102
	v_mul_f32_e32 v38, 0x3e38aa3b, v38
	v_cndmask_b32_e32 v37, v89, v37, vcc
	v_cmp_gt_u32_e32 vcc, s7, v95
	v_add_u32_e32 v95, v134, v103
	v_mul_f32_e32 v39, 0x3e38aa3b, v39
	v_cndmask_b32_e32 v38, v89, v38, vcc
	v_cmp_gt_u32_e32 vcc, s7, v95
	v_add_u32_e32 v95, v134, v104
	v_mfma_f32_32x32x16_bf16 v[16:31], v[114:117], v[126:129], v[16:31]
	v_cndmask_b32_e32 v39, v89, v39, vcc
	v_mul_f32_e32 v40, 0x3e38aa3b, v40
	v_cmp_gt_u32_e32 vcc, s7, v95
	v_add_u32_e32 v95, v134, v105
	v_mul_f32_e32 v41, 0x3e38aa3b, v41
	v_cndmask_b32_e32 v40, v89, v40, vcc
	v_cmp_gt_u32_e32 vcc, s7, v95
	v_add_u32_e32 v95, v134, v106
	v_mul_f32_e32 v42, 0x3e38aa3b, v42
	v_cndmask_b32_e32 v41, v89, v41, vcc
	v_cmp_gt_u32_e32 vcc, s7, v95
	v_add_u32_e32 v95, v134, v107
	v_mul_f32_e32 v43, 0x3e38aa3b, v43
	v_cndmask_b32_e32 v42, v89, v42, vcc
	v_cmp_gt_u32_e32 vcc, s7, v95
	v_add_u32_e32 v95, v134, v108
	v_mul_f32_e32 v44, 0x3e38aa3b, v44
	v_cndmask_b32_e32 v43, v89, v43, vcc
	v_cmp_gt_u32_e32 vcc, s7, v95
	v_add_u32_e32 v95, v134, v109
	v_mul_f32_e32 v45, 0x3e38aa3b, v45
	v_cndmask_b32_e32 v44, v89, v44, vcc
	v_cmp_gt_u32_e32 vcc, s7, v95
	v_add_u32_e32 v95, v134, v110
	v_mul_f32_e32 v46, 0x3e38aa3b, v46
	v_cndmask_b32_e32 v45, v89, v45, vcc
	v_cmp_gt_u32_e32 vcc, s7, v95
	v_add_u32_e32 v95, v134, v111
	v_mul_f32_e32 v47, 0x3e38aa3b, v47
	v_cndmask_b32_e32 v46, v89, v46, vcc
	v_cmp_gt_u32_e32 vcc, s7, v95
	v_add_u32_e32 v95, 32, v94
	v_mul_f32_e32 v16, 0x3e38aa3b, v16
	v_cndmask_b32_e32 v47, v89, v47, vcc
	v_cmp_gt_u32_e32 vcc, s7, v95
	v_add_u32_e32 v95, 33, v94
	v_mul_f32_e32 v17, 0x3e38aa3b, v17
	v_cndmask_b32_e32 v16, v89, v16, vcc
	v_cmp_gt_u32_e32 vcc, s7, v95
	v_add_u32_e32 v95, 34, v94
	v_mul_f32_e32 v18, 0x3e38aa3b, v18
	v_cndmask_b32_e32 v17, v89, v17, vcc
	v_cmp_gt_u32_e32 vcc, s7, v95
	v_add_u32_e32 v95, 35, v94
	v_mul_f32_e32 v19, 0x3e38aa3b, v19
	v_cndmask_b32_e32 v18, v89, v18, vcc
	v_cmp_gt_u32_e32 vcc, s7, v95
	v_add_u32_e32 v95, 40, v94
	v_mul_f32_e32 v20, 0x3e38aa3b, v20
	v_cndmask_b32_e32 v19, v89, v19, vcc
	v_cmp_gt_u32_e32 vcc, s7, v95
	v_add_u32_e32 v95, 41, v94
	v_mul_f32_e32 v21, 0x3e38aa3b, v21
	v_cndmask_b32_e32 v20, v89, v20, vcc
	v_cmp_gt_u32_e32 vcc, s7, v95
	v_add_u32_e32 v95, 42, v94
	v_mul_f32_e32 v22, 0x3e38aa3b, v22
	v_cndmask_b32_e32 v21, v89, v21, vcc
	v_cmp_gt_u32_e32 vcc, s7, v95
	v_add_u32_e32 v95, 43, v94
	v_mul_f32_e32 v23, 0x3e38aa3b, v23
	v_cndmask_b32_e32 v22, v89, v22, vcc
	v_cmp_gt_u32_e32 vcc, s7, v95
	v_add_u32_e32 v95, 48, v94
	v_max3_f32 v34, v34, v36, v37
	v_cndmask_b32_e32 v23, v89, v23, vcc
	v_mul_f32_e32 v24, 0x3e38aa3b, v24
	v_cmp_gt_u32_e32 vcc, s7, v95
	v_add_u32_e32 v95, 49, v94
	v_max3_f32 v34, v34, v38, v39
	v_cndmask_b32_e32 v24, v89, v24, vcc
	v_mul_f32_e32 v25, 0x3e38aa3b, v25
	v_cmp_gt_u32_e32 vcc, s7, v95
	v_add_u32_e32 v95, 50, v94
	v_max3_f32 v34, v34, v40, v41
	v_cndmask_b32_e32 v25, v89, v25, vcc
	v_mul_f32_e32 v26, 0x3e38aa3b, v26
	v_cmp_gt_u32_e32 vcc, s7, v95
	v_add_u32_e32 v95, 51, v94
	v_max3_f32 v34, v34, v42, v43
	v_cndmask_b32_e32 v26, v89, v26, vcc
	v_mul_f32_e32 v27, 0x3e38aa3b, v27
	v_cmp_gt_u32_e32 vcc, s7, v95
	v_add_u32_e32 v95, 56, v94
	v_max3_f32 v34, v34, v44, v45
	v_cndmask_b32_e32 v27, v89, v27, vcc
	v_mul_f32_e32 v28, 0x3e38aa3b, v28
	v_cmp_gt_u32_e32 vcc, s7, v95
	v_add_u32_e32 v95, 57, v94
	v_max3_f32 v34, v34, v46, v47
	v_cndmask_b32_e32 v28, v89, v28, vcc
	v_mul_f32_e32 v29, 0x3e38aa3b, v29
	v_cmp_gt_u32_e32 vcc, s7, v95
	v_add_u32_e32 v95, 58, v94
	v_max3_f32 v34, v34, v16, v17
	v_cndmask_b32_e32 v29, v89, v29, vcc
	v_mul_f32_e32 v30, 0x3e38aa3b, v30
	v_cmp_gt_u32_e32 vcc, s7, v95
	v_add_u32_e32 v95, 59, v94
	v_max3_f32 v34, v34, v18, v19
	v_cndmask_b32_e32 v30, v89, v30, vcc
	v_mul_f32_e32 v31, 0x3e38aa3b, v31
	v_cmp_gt_u32_e32 vcc, s7, v95
	v_add_u32_e32 v95, 64, v94
	v_add_u32_e32 v97, 0x80, v93
	v_max3_f32 v34, v34, v20, v21
	v_cndmask_b32_e32 v31, v89, v31, vcc
	v_cmp_gt_u32_e32 vcc, s64, v97
	v_cmp_gt_u32_e64 s[4:5], s7, v95
	v_max3_f32 v34, v34, v22, v23
	v_mul_f32_e32 v0, 0x3e38aa3b, v0
	s_and_b64 vcc, vcc, s[4:5]
	v_max3_f32 v34, v34, v24, v25
	v_cndmask_b32_e32 v98, v89, v0, vcc
	v_add_u32_e32 v0, 0x41, v94
	v_max3_f32 v34, v34, v26, v27
	v_cmp_lt_u32_e32 vcc, s68, v93
	v_cmp_gt_u32_e64 s[4:5], s7, v0
	v_max3_f32 v34, v34, v28, v29
	v_mul_f32_e32 v0, 0x3e38aa3b, v1
	s_and_b64 vcc, vcc, s[4:5]
	v_max3_f32 v34, v34, v30, v31
	v_cndmask_b32_e32 v99, v89, v0, vcc
	v_max3_f32 v0, v34, v98, v99
	v_add_u32_e32 v1, 0x42, v94
	v_add_u32_e32 v34, 0x82, v93
	v_cmp_gt_u32_e32 vcc, s64, v34
	v_cmp_gt_u32_e64 s[4:5], s7, v1
; __device__ __forceinline__ float shfl_idx(float v, int srclane) { return __int_as_float(__builtin_amdgcn_ds_bpermute(srclane << 2, __float_as_int(v))); }
; __device__ __forceinline__ int crow(int r, int hi) { return (r & 3) + 8 * (r >> 2) + 4 * hi; }
; __device__ __forceinline__ void dil_wave_item(const bf16* __restrict__ qkv, bf16* __restrict__ odil, float* __restrict__ lse,
;                               int pat, int g  , int head, char* wl  , const int W) {
;     ...
;   float mx = -1e30f;
; #pragma unroll
;   for (int kb = 0; kb < 5; ++kb)
; #pragma unroll
;     for (int r = 0; r < 16; ++r) {
;       const int rel = kb * 32 - 64 + crow(r, hi) - r32;
;       const int kc = i0 + r32 + rel;
;       const bool ok = (rel >= -64) && (rel <= 64) && (kc >= 0) && (kc < L);
;       const float s = ok ? sc[kb][r] * AC : -1e30f;
;       sc[kb][r] = s; mx = fmaxf(mx, s);
;     }
;   mx = fmaxf(mx, shfl_idx(mx, lane ^ 32));
;   float ls = 0.f;
; #pragma unroll
;   for (int kb = 0; kb < 5; ++kb)
; #pragma unroll
;     for (int r = 0; r < 16; ++r) { const float e = __builtin_amdgcn_exp2f(sc[kb][r] - mx); sc[kb][r] = e; ls += e; }
;   ls += shfl_idx(ls, lane ^ 32);
	v_mul_f32_e32 v1, 0x3e38aa3b, v2
	s_and_b64 vcc, vcc, s[4:5]
	v_cndmask_b32_e32 v100, v89, v1, vcc
	v_add_u32_e32 v1, 0x43, v94
	v_add_u32_e32 v2, 0x83, v93
	v_cmp_gt_u32_e32 vcc, s64, v2
	v_cmp_gt_u32_e64 s[4:5], s7, v1
	v_mul_f32_e32 v1, 0x3e38aa3b, v3
	s_and_b64 vcc, vcc, s[4:5]
	v_cndmask_b32_e32 v101, v89, v1, vcc
	v_add_u32_e32 v1, 0x48, v94
	v_add_u32_e32 v2, 0x88, v93
	v_cmp_gt_u32_e32 vcc, s64, v2
	v_cmp_gt_u32_e64 s[4:5], s7, v1
	v_mul_f32_e32 v1, 0x3e38aa3b, v4
	s_and_b64 vcc, vcc, s[4:5]
	v_cndmask_b32_e32 v102, v89, v1, vcc
	v_add_u32_e32 v1, 0x49, v94
	v_add_u32_e32 v2, 0x89, v93
	v_cmp_gt_u32_e32 vcc, s64, v2
	v_cmp_gt_u32_e64 s[4:5], s7, v1
	v_mul_f32_e32 v1, 0x3e38aa3b, v5
	s_and_b64 vcc, vcc, s[4:5]
	v_cndmask_b32_e32 v103, v89, v1, vcc
	v_add_u32_e32 v1, 0x4a, v94
	v_add_u32_e32 v2, 0x8a, v93
	v_cmp_gt_u32_e32 vcc, s64, v2
	v_cmp_gt_u32_e64 s[4:5], s7, v1
	v_mul_f32_e32 v1, 0x3e38aa3b, v6
	s_and_b64 vcc, vcc, s[4:5]
	v_cndmask_b32_e32 v104, v89, v1, vcc
	v_add_u32_e32 v1, 0x4b, v94
	v_add_u32_e32 v2, 0x8b, v93
	v_cmp_gt_u32_e32 vcc, s64, v2
	v_cmp_gt_u32_e64 s[4:5], s7, v1
	v_mul_f32_e32 v1, 0x3e38aa3b, v7
	s_and_b64 vcc, vcc, s[4:5]
	v_cndmask_b32_e32 v105, v89, v1, vcc
	v_add_u32_e32 v1, 0x50, v94
	v_add_u32_e32 v2, 0x90, v93
	v_cmp_gt_u32_e32 vcc, s64, v2
	v_cmp_gt_u32_e64 s[4:5], s7, v1
	v_mul_f32_e32 v1, 0x3e38aa3b, v8
	s_and_b64 vcc, vcc, s[4:5]
	v_cndmask_b32_e32 v106, v89, v1, vcc
	v_add_u32_e32 v1, 0x51, v94
	v_add_u32_e32 v2, 0x91, v93
	v_cmp_gt_u32_e32 vcc, s64, v2
	v_cmp_gt_u32_e64 s[4:5], s7, v1
	v_mul_f32_e32 v1, 0x3e38aa3b, v9
	s_and_b64 vcc, vcc, s[4:5]
	v_cndmask_b32_e32 v107, v89, v1, vcc
	v_add_u32_e32 v1, 0x52, v94
	v_add_u32_e32 v2, 0x92, v93
	v_cmp_gt_u32_e32 vcc, s64, v2
	v_cmp_gt_u32_e64 s[4:5], s7, v1
	v_mul_f32_e32 v1, 0x3e38aa3b, v10
	s_and_b64 vcc, vcc, s[4:5]
	v_cndmask_b32_e32 v108, v89, v1, vcc
	v_add_u32_e32 v1, 0x53, v94
	v_add_u32_e32 v2, 0x93, v93
	v_cmp_gt_u32_e32 vcc, s64, v2
	v_cmp_gt_u32_e64 s[4:5], s7, v1
	v_mul_f32_e32 v1, 0x3e38aa3b, v11
	s_and_b64 vcc, vcc, s[4:5]
	v_cndmask_b32_e32 v109, v89, v1, vcc
	v_add_u32_e32 v1, 0x58, v94
	v_add_u32_e32 v2, 0x98, v93
	v_cmp_gt_u32_e32 vcc, s64, v2
	v_cmp_gt_u32_e64 s[4:5], s7, v1
	v_mul_f32_e32 v1, 0x3e38aa3b, v12
	s_and_b64 vcc, vcc, s[4:5]
	v_cndmask_b32_e32 v110, v89, v1, vcc
	v_add_u32_e32 v1, 0x59, v94
	v_add_u32_e32 v2, 0x99, v93
	v_cmp_gt_u32_e32 vcc, s64, v2
	v_cmp_gt_u32_e64 s[4:5], s7, v1
	v_mul_f32_e32 v1, 0x3e38aa3b, v13
	s_and_b64 vcc, vcc, s[4:5]
	v_cndmask_b32_e32 v111, v89, v1, vcc
	v_add_u32_e32 v1, 0x5a, v94
	v_add_u32_e32 v2, 0x9a, v93
	v_max3_f32 v0, v0, v100, v101
	v_cmp_gt_u32_e32 vcc, s64, v2
	v_cmp_gt_u32_e64 s[4:5], s7, v1
	v_max3_f32 v0, v0, v102, v103
	v_mul_f32_e32 v1, 0x3e38aa3b, v14
	s_and_b64 vcc, vcc, s[4:5]
	v_max3_f32 v0, v0, v104, v105
	v_cndmask_b32_e32 v112, v89, v1, vcc
	v_add_u32_e32 v1, 0x5b, v94
	v_add_u32_e32 v2, 0x9b, v93
	v_max3_f32 v0, v0, v106, v107
	v_cmp_gt_u32_e32 vcc, s64, v2
	v_cmp_gt_u32_e64 s[4:5], s7, v1
	v_max3_f32 v0, v0, v108, v109
	v_mul_f32_e32 v1, 0x3e38aa3b, v15
	s_and_b64 vcc, vcc, s[4:5]
	v_max3_f32 v0, v0, v110, v111
	v_cndmask_b32_e32 v113, v89, v1, vcc
	v_lshlrev_b32_e32 v1, 2, v87
	v_max3_f32 v0, v0, v112, v113
	v_xor_b32_e32 v114, 0x80, v1
	ds_bpermute_b32 v1, v114, v0
	s_waitcnt lgkmcnt(0)
	v_max_f32_e32 v1, v1, v1
	v_max_f32_e32 v34, v0, v1
	v_sub_f32_e32 v0, v64, v34
	v_exp_f32_e32 v115, v0
	v_sub_f32_e32 v0, v65, v34
	v_exp_f32_e32 v116, v0
	v_sub_f32_e32 v0, v66, v34
	v_exp_f32_e32 v117, v0
	v_sub_f32_e32 v0, v67, v34
	v_exp_f32_e32 v118, v0
	v_sub_f32_e32 v1, v68, v34
	v_add_f32_e32 v0, 0, v115
	v_exp_f32_e32 v119, v1
	v_sub_f32_e32 v1, v69, v34
	v_add_f32_e32 v0, v116, v0
	v_exp_f32_e32 v120, v1
	v_sub_f32_e32 v1, v70, v34
	v_add_f32_e32 v0, v117, v0
	v_exp_f32_e32 v121, v1
	v_sub_f32_e32 v1, v71, v34
	v_add_f32_e32 v0, v118, v0
	v_exp_f32_e32 v122, v1
	v_sub_f32_e32 v1, v72, v34
	v_add_f32_e32 v0, v119, v0
	v_exp_f32_e32 v123, v1
	v_sub_f32_e32 v1, v73, v34
	v_add_f32_e32 v0, v120, v0
	v_exp_f32_e32 v124, v1
	v_sub_f32_e32 v1, v74, v34
	v_add_f32_e32 v0, v121, v0
	v_exp_f32_e32 v125, v1
	v_sub_f32_e32 v1, v75, v34
	v_add_f32_e32 v0, v122, v0
	v_exp_f32_e32 v126, v1
	v_sub_f32_e32 v1, v76, v34
	v_add_f32_e32 v0, v123, v0
	v_exp_f32_e32 v127, v1
	v_sub_f32_e32 v1, v77, v34
	v_add_f32_e32 v0, v124, v0
	v_exp_f32_e32 v128, v1
	v_sub_f32_e32 v1, v78, v34
	v_add_f32_e32 v0, v125, v0
	v_exp_f32_e32 v129, v1
	v_sub_f32_e32 v1, v79, v34
	v_add_f32_e32 v0, v126, v0
	v_exp_f32_e32 v130, v1
	v_sub_f32_e32 v1, v48, v34
	v_add_f32_e32 v0, v127, v0
	v_exp_f32_e32 v131, v1
	v_sub_f32_e32 v1, v49, v34
	v_add_f32_e32 v0, v128, v0
	v_exp_f32_e32 v132, v1
	v_sub_f32_e32 v1, v50, v34
	v_add_f32_e32 v0, v129, v0
	v_exp_f32_e32 v133, v1
	v_sub_f32_e32 v1, v51, v34
	v_add_f32_e32 v0, v130, v0
	v_exp_f32_e32 v134, v1
	v_sub_f32_e32 v1, v52, v34
	v_add_f32_e32 v0, v131, v0
	v_exp_f32_e32 v135, v1
	v_sub_f32_e32 v1, v53, v34
	v_add_f32_e32 v0, v132, v0
	v_exp_f32_e32 v136, v1
	v_sub_f32_e32 v1, v54, v34
	v_add_f32_e32 v0, v133, v0
	v_exp_f32_e32 v137, v1
	v_sub_f32_e32 v1, v55, v34
	v_add_f32_e32 v0, v134, v0
	v_exp_f32_e32 v138, v1
	v_sub_f32_e32 v1, v56, v34
	v_add_f32_e32 v0, v135, v0
	v_exp_f32_e32 v139, v1
	v_sub_f32_e32 v1, v57, v34
	v_add_f32_e32 v0, v136, v0
	v_exp_f32_e32 v140, v1
	v_sub_f32_e32 v1, v58, v34
	v_add_f32_e32 v0, v137, v0
	v_exp_f32_e32 v141, v1
	v_sub_f32_e32 v1, v59, v34
	v_add_f32_e32 v0, v138, v0
	v_exp_f32_e32 v142, v1
	v_sub_f32_e32 v1, v60, v34
	v_add_f32_e32 v0, v139, v0
	v_exp_f32_e32 v143, v1
	v_sub_f32_e32 v1, v61, v34
	v_add_f32_e32 v0, v140, v0
; __device__ __forceinline__ float shfl_idx(float v, int srclane) { return __int_as_float(__builtin_amdgcn_ds_bpermute(srclane << 2, __float_as_int(v))); }
; __device__ __forceinline__ int v_st2(int k, int c) { const int kk = (k & ~0xC) | ((k & 4) << 1) | ((k & 8) >> 1); return ((kk >> 3) * 2 + (c >> 5)) * 512 + ((kk & 7) * 32 + (c & 31)) * 2; }
; __device__ __forceinline__ int v_rd_base(int lane) { return ((lane & 3) << 3) | (((lane >> 2) & 3) << 6) | (((lane >> 4) & 1) << 5) | (((lane >> 5) & 1) << 8); }
; __device__ __forceinline__ void dil_wave_item(const bf16* __restrict__ qkv, bf16* __restrict__ odil, float* __restrict__ lse,
;                               int pat, int g  , int head, char* wl  , const int W) {
;     ...
;   float ls = 0.f;
; #pragma unroll
;   for (int kb = 0; kb < 5; ++kb)
; #pragma unroll
;     for (int r = 0; r < 16; ++r) { const float e = __builtin_amdgcn_exp2f(sc[kb][r] - mx); sc[kb][r] = e; ls += e; }
;   ls += shfl_idx(ls, lane ^ 32);
;   f32x16 o0 = {}, o1 = {};
;   const int vb = (int)(uintptr_t)wl + v_rd_base(lane);
; #pragma unroll
;   for (int kb = 0; kb < 5; ++kb) {
;     bf16x8 vr[4];
; #pragma unroll
;     for (int i = 0; i < 4; ++i) {
;       const int key = i * 8 + (lane >> 3);
;       int kc = i0 - 64 + kb * 32 + key; kc = min(max(kc, 0), L - 1);
;       vr[i] = *reinterpret_cast<const bf16x8*>(qkv + (size_t)(tbase + kc * dil) * LDQ + 2560 + head * 64 + (lane & 7) * 8);
;     }
; #pragma unroll
;     for (int i = 0; i < 4; ++i) *reinterpret_cast<bf16x8*>(wl + v_st2(i * 8 + (lane >> 3), (lane & 7) * 8)) = vr[i];
	v_exp_f32_e32 v144, v1
	v_sub_f32_e32 v1, v62, v34
	v_add_f32_e32 v0, v141, v0
	v_exp_f32_e32 v145, v1
	v_sub_f32_e32 v1, v63, v34
	v_add_f32_e32 v0, v142, v0
	v_exp_f32_e32 v146, v1
	v_sub_f32_e32 v1, v32, v34
	v_add_f32_e32 v0, v143, v0
	v_exp_f32_e32 v56, v1
	v_sub_f32_e32 v1, v33, v34
	v_add_f32_e32 v0, v144, v0
	v_exp_f32_e32 v57, v1
	v_sub_f32_e32 v1, v96, v34
	v_add_f32_e32 v0, v145, v0
	v_exp_f32_e32 v60, v1
	v_sub_f32_e32 v1, v35, v34
	v_add_f32_e32 v0, v146, v0
	v_exp_f32_e32 v65, v1
	v_sub_f32_e32 v1, v36, v34
	v_add_f32_e32 v0, v56, v0
	v_exp_f32_e32 v69, v1
	v_sub_f32_e32 v1, v37, v34
	v_add_f32_e32 v0, v57, v0
	v_exp_f32_e32 v71, v1
	v_sub_f32_e32 v1, v38, v34
	v_add_f32_e32 v0, v60, v0
	v_exp_f32_e32 v75, v1
	v_sub_f32_e32 v1, v39, v34
	v_add_f32_e32 v0, v65, v0
	v_exp_f32_e32 v78, v1
	v_sub_f32_e32 v1, v40, v34
	v_add_f32_e32 v0, v69, v0
	v_exp_f32_e32 v72, v1
	v_sub_f32_e32 v1, v41, v34
	v_add_f32_e32 v0, v71, v0
	v_exp_f32_e32 v76, v1
	v_sub_f32_e32 v1, v42, v34
	v_add_f32_e32 v0, v75, v0
	v_exp_f32_e32 v79, v1
	v_sub_f32_e32 v1, v43, v34
	v_add_f32_e32 v0, v78, v0
	v_exp_f32_e32 v93, v1
	v_sub_f32_e32 v1, v44, v34
	v_add_f32_e32 v0, v72, v0
	v_exp_f32_e32 v94, v1
	v_sub_f32_e32 v1, v45, v34
	v_add_f32_e32 v0, v76, v0
	v_exp_f32_e32 v95, v1
	v_sub_f32_e32 v1, v46, v34
	v_add_f32_e32 v0, v79, v0
	v_exp_f32_e32 v96, v1
	v_sub_f32_e32 v1, v47, v34
	v_add_f32_e32 v0, v93, v0
	v_exp_f32_e32 v97, v1
	v_sub_f32_e32 v1, v16, v34
	v_add_f32_e32 v0, v94, v0
	v_exp_f32_e32 v35, v1
	v_sub_f32_e32 v1, v17, v34
	v_add_f32_e32 v0, v95, v0
	v_exp_f32_e32 v36, v1
	v_sub_f32_e32 v1, v18, v34
	v_add_f32_e32 v0, v96, v0
	v_exp_f32_e32 v37, v1
	v_sub_f32_e32 v1, v19, v34
	v_add_f32_e32 v0, v97, v0
	v_exp_f32_e32 v38, v1
	v_sub_f32_e32 v1, v20, v34
	v_add_f32_e32 v0, v35, v0
	v_exp_f32_e32 v42, v1
	v_sub_f32_e32 v1, v21, v34
	v_add_f32_e32 v0, v36, v0
	v_exp_f32_e32 v43, v1
	v_sub_f32_e32 v1, v22, v34
	v_add_f32_e32 v0, v37, v0
	v_exp_f32_e32 v45, v1
	v_sub_f32_e32 v1, v23, v34
	v_add_f32_e32 v0, v38, v0
	v_exp_f32_e32 v47, v1
	v_sub_f32_e32 v1, v24, v34
	v_add_f32_e32 v0, v42, v0
	v_exp_f32_e32 v44, v1
	v_sub_f32_e32 v1, v25, v34
	v_add_f32_e32 v0, v43, v0
	v_exp_f32_e32 v46, v1
	v_sub_f32_e32 v1, v26, v34
	v_add_f32_e32 v0, v45, v0
	v_exp_f32_e32 v48, v1
	v_sub_f32_e32 v1, v27, v34
	v_add_f32_e32 v0, v47, v0
	v_exp_f32_e32 v49, v1
	v_add_f32_e32 v0, v44, v0
	v_add_f32_e32 v0, v46, v0
	v_add_f32_e32 v0, v48, v0
	v_bfe_u32 v17, v92, 3, 3
	v_add_f32_e32 v16, v49, v0
	v_sub_f32_e32 v0, v28, v34
	v_or_b32_e32 v10, s78, v17
	v_exp_f32_e32 v50, v0
	v_sub_f32_e32 v0, v29, v34
	v_subrev_u32_e32 v39, 64, v10
	v_lshlrev_b32_e32 v18, 3, v92
	v_exp_f32_e32 v51, v0
	v_and_b32_e32 v2, 56, v18
	v_max_i32_e32 v0, 0, v39
	v_min_u32_e32 v0, s6, v0
	v_lshlrev_b32_e32 v32, 1, v2
	v_subrev_u32_e32 v2, 56, v10
	v_lshlrev_b32_e32 v0, s71, v0
	v_max_i32_e32 v2, 0, v2
	v_add_u32_e32 v0, s79, v0
	v_min_u32_e32 v2, s6, v2
	v_subrev_u32_e32 v8, 48, v10
	v_mad_i64_i32 v[0:1], s[4:5], v0, s62, v[84:85]
	v_lshlrev_b32_e32 v2, s71, v2
	v_max_i32_e32 v8, 0, v8
	v_lshl_add_u64 v[0:1], v[0:1], 0, s[74:75]
	v_mov_b32_e32 v33, v83
	v_add_u32_e32 v2, s79, v2
	v_min_u32_e32 v8, s6, v8
	v_subrev_u32_e32 v10, 40, v10
	v_lshl_add_u64 v[0:1], v[0:1], 0, v[32:33]
	v_mad_i64_i32 v[2:3], s[4:5], v2, s62, v[84:85]
	v_lshlrev_b32_e32 v8, s71, v8
	v_max_i32_e32 v10, 0, v10
	v_add_co_u32_e32 v0, vcc, s63, v0
	v_lshl_add_u64 v[2:3], v[2:3], 0, s[74:75]
	v_add_u32_e32 v8, s79, v8
	v_min_u32_e32 v10, s6, v10
	v_addc_co_u32_e32 v1, vcc, 0, v1, vcc
	v_lshl_add_u64 v[2:3], v[2:3], 0, v[32:33]
	v_mad_i64_i32 v[8:9], s[4:5], v8, s62, v[84:85]
	v_lshlrev_b32_e32 v10, s71, v10
	v_add_co_u32_e32 v4, vcc, s63, v2
	v_lshl_add_u64 v[8:9], v[8:9], 0, s[74:75]
	v_add_u32_e32 v10, s79, v10
	v_addc_co_u32_e32 v5, vcc, 0, v3, vcc
	v_lshl_add_u64 v[8:9], v[8:9], 0, v[32:33]
	v_mad_i64_i32 v[10:11], s[4:5], v10, s62, v[84:85]
	v_add_co_u32_e32 v8, vcc, s63, v8
	v_lshl_add_u64 v[10:11], v[10:11], 0, s[74:75]
	s_nop 0
	v_addc_co_u32_e32 v9, vcc, 0, v9, vcc
	v_lshl_add_u64 v[10:11], v[10:11], 0, v[32:33]
	v_add_co_u32_e32 v12, vcc, s63, v10
	s_nop 0
	v_addc_co_u32_e32 v13, vcc, 0, v11, vcc
	s_nop 0
	v_sub_f32_e32 v19, v30, v34
	v_exp_f32_e32 v147, v19
	v_sub_f32_e32 v19, v31, v34
	v_exp_f32_e32 v148, v19
	v_sub_f32_e32 v19, v98, v34
	v_add_f32_e32 v16, v50, v16
	v_exp_f32_e32 v52, v19
	v_sub_f32_e32 v19, v99, v34
	v_add_f32_e32 v16, v51, v16
	v_exp_f32_e32 v53, v19
	v_sub_f32_e32 v19, v100, v34
	v_add_f32_e32 v16, v147, v16
	v_exp_f32_e32 v54, v19
	v_sub_f32_e32 v19, v101, v34
	v_add_f32_e32 v16, v148, v16
	v_exp_f32_e32 v55, v19
	v_sub_f32_e32 v19, v102, v34
	v_add_f32_e32 v16, v52, v16
	v_exp_f32_e32 v58, v19
	v_sub_f32_e32 v19, v103, v34
	v_add_f32_e32 v16, v53, v16
	v_exp_f32_e32 v61, v19
	v_sub_f32_e32 v19, v104, v34
	v_add_f32_e32 v16, v54, v16
	v_exp_f32_e32 v63, v19
	v_sub_f32_e32 v19, v105, v34
	v_add_f32_e32 v16, v55, v16
	v_exp_f32_e32 v66, v19
	v_sub_f32_e32 v19, v106, v34
	v_add_f32_e32 v16, v58, v16
	v_exp_f32_e32 v59, v19
	v_sub_f32_e32 v19, v107, v34
	v_add_f32_e32 v16, v61, v16
	v_exp_f32_e32 v62, v19
	v_sub_f32_e32 v19, v108, v34
	v_add_f32_e32 v16, v63, v16
	v_exp_f32_e32 v64, v19
	v_sub_f32_e32 v19, v109, v34
	v_add_f32_e32 v16, v66, v16
	v_exp_f32_e32 v67, v19
	v_sub_f32_e32 v19, v110, v34
	v_add_f32_e32 v16, v59, v16
	v_exp_f32_e32 v70, v19
	v_sub_f32_e32 v19, v111, v34
	v_add_f32_e32 v16, v62, v16
	v_exp_f32_e32 v73, v19
	v_sub_f32_e32 v19, v112, v34
	v_add_f32_e32 v16, v64, v16
	v_exp_f32_e32 v74, v19
	v_sub_f32_e32 v19, v113, v34
	v_add_f32_e32 v16, v67, v16
	v_exp_f32_e32 v77, v19
	v_add_f32_e32 v16, v70, v16
	v_add_f32_e32 v16, v73, v16
	v_add_f32_e32 v16, v74, v16
	v_lshlrev_b32_e32 v19, 4, v92
	v_add_f32_e32 v40, v77, v16
	v_lshlrev_b32_e32 v16, 3, v87
	v_and_b32_e32 v20, 0xc0, v19
	v_lshlrev_b32_e32 v21, 1, v92
	v_and_or_b32 v20, v16, 24, v20
	v_and_b32_e32 v21, 32, v21
	v_and_b32_e32 v16, 0x100, v16
	v_or3_b32 v16, v20, v21, v16
	v_add_u32_e32 v68, s55, v16
	v_bfe_u32 v16, v18, 5, 1
	v_and_b32_e32 v18, 48, v19
	v_lshrrev_b32_e32 v19, 4, v92
	v_and_or_b32 v16, v19, 2, v16
	v_lshlrev_b32_e32 v17, 6, v17
	v_and_or_b32 v19, v17, s69, v18
	v_lshl_add_u32 v16, v16, 9, s55
	v_add_u32_e32 v149, v16, v19
	ds_bpermute_b32 v41, v114, v40
	s_waitcnt vmcnt(16)
; #define SBAR() __builtin_amdgcn_sched_barrier(0)
; __device__ __forceinline__ int v_st2(int k, int c) { const int kk = (k & ~0xC) | ((k & 4) << 1) | ((k & 8) >> 1); return ((kk >> 3) * 2 + (c >> 5)) * 512 + ((kk & 7) * 32 + (c & 31)) * 2; }
; __device__ __forceinline__ void dil_wave_item(const bf16* __restrict__ qkv, bf16* __restrict__ odil, float* __restrict__ lse,
;                               int pat, int g  , int head, char* wl  , const int W) {
;     ...
; #pragma unroll
;   for (int kb = 0; kb < 5; ++kb) {
;     bf16x8 vr[4];
; #pragma unroll
;     for (int i = 0; i < 4; ++i) {
;       const int key = i * 8 + (lane >> 3);
;       int kc = i0 - 64 + kb * 32 + key; kc = min(max(kc, 0), L - 1);
;       vr[i] = *reinterpret_cast<const bf16x8*>(qkv + (size_t)(tbase + kc * dil) * LDQ + 2560 + head * 64 + (lane & 7) * 8);
;     }
; #pragma unroll
;     for (int i = 0; i < 4; ++i) *reinterpret_cast<bf16x8*>(wl + v_st2(i * 8 + (lane >> 3), (lane & 7) * 8)) = vr[i];
;     bf16x8 pa0, pa1;
;     PK4(sc[kb], 0, pa0); PK4(sc[kb], 8, pa1);
;     asm volatile("s_waitcnt lgkmcnt(0)" ::: "memory");
;     const s16x4 a0 = tr_read<v_rd_off2(0, 0, 0)>(vb), b0 = tr_read<v_rd_off2(0, 0, 1)>(vb), a1 = tr_read<v_rd_off2(0, 1, 0)>(vb), b1 = tr_read<v_rd_off2(0, 1, 1)>(vb);
;     const s16x4 c0 = tr_read<v_rd_off2(1, 0, 0)>(vb), d0_ = tr_read<v_rd_off2(1, 0, 1)>(vb), c1 = tr_read<v_rd_off2(1, 1, 0)>(vb), d1 = tr_read<v_rd_off2(1, 1, 1)>(vb);
;     asm volatile("s_waitcnt lgkmcnt(0)" ::: "memory"); SBAR();
;     o0 = __builtin_amdgcn_mfma_f32_32x32x16_bf16(pa0, PKV(a0, b0), o0, 0, 0, 0);
;     o0 = __builtin_amdgcn_mfma_f32_32x32x16_bf16(pa1, PKV(a1, b1), o0, 0, 0, 0);
;     o1 = __builtin_amdgcn_mfma_f32_32x32x16_bf16(pa0, PKV(c0, d0_), o1, 0, 0, 0);
;     o1 = __builtin_amdgcn_mfma_f32_32x32x16_bf16(pa1, PKV(c1, d1), o1, 0, 0, 0);
;     SBAR();
;   }
;   if (hi == 0) lse[((size_t)pat * T + tbase + (i0 + r32) * dil) * 8 + head] = mx + __log2f(ls);
	ds_write_b128 v149, v[152:155]
	v_or3_b32 v0, v17, v18, s61
	v_add_u32_e32 v150, v16, v0
	ds_write_b128 v150, v[156:159]
	ds_write_b128 v149, v[160:163] offset:2048
	ds_write_b128 v150, v[164:167] offset:2048
	v_cvt_pk_bf16_f32 v16, v115, v116
	v_cvt_pk_bf16_f32 v17, v117, v118
	v_cvt_pk_bf16_f32 v18, v119, v120
	v_cvt_pk_bf16_f32 v19, v121, v122
	v_cvt_pk_bf16_f32 v98, v123, v124
	v_cvt_pk_bf16_f32 v99, v125, v126
	v_cvt_pk_bf16_f32 v100, v127, v128
	v_cvt_pk_bf16_f32 v101, v129, v130
	s_waitcnt lgkmcnt(0)
	ds_read_b64_tr_b16 v[0:1], v68 offset:0
	ds_read_b64_tr_b16 v[2:3], v68 offset:0x400
	ds_read_b64_tr_b16 v[20:21], v68 offset:0x800
	ds_read_b64_tr_b16 v[22:23], v68 offset:0xc00
	ds_read_b64_tr_b16 v[24:25], v68 offset:0x200
	ds_read_b64_tr_b16 v[26:27], v68 offset:0x600
	ds_read_b64_tr_b16 v[102:103], v68 offset:0xa00
	ds_read_b64_tr_b16 v[104:105], v68 offset:0xe00
	s_waitcnt lgkmcnt(0)
	s_nop 0
	v_permlane32_swap_b32_e32 v16, v18
	v_permlane32_swap_b32_e32 v17, v19
	v_permlane32_swap_b32_e32 v98, v100
	v_permlane32_swap_b32_e32 v99, v101
	v_mfma_f32_32x32x16_bf16 v[0:15], v[16:19], v[0:3], 0
	s_nop 0
	v_mfma_f32_32x32x16_bf16 v[0:15], v[98:101], v[20:23], v[0:15]
	v_mfma_f32_32x32x16_bf16 v[16:31], v[16:19], v[24:27], 0
	v_mfma_f32_32x32x16_bf16 v[16:31], v[98:101], v[102:105], v[16:31]
	s_waitcnt vmcnt(12)
	ds_write_b128 v149, v[168:171]
	ds_write_b128 v150, v[172:175]
	ds_write_b128 v149, v[176:179] offset:2048
	ds_write_b128 v150, v[180:183] offset:2048
	v_cvt_pk_bf16_f32 v98, v131, v132
	v_cvt_pk_bf16_f32 v99, v133, v134
	v_cvt_pk_bf16_f32 v100, v135, v136
	v_cvt_pk_bf16_f32 v101, v137, v138
	v_cvt_pk_bf16_f32 v102, v139, v140
	v_cvt_pk_bf16_f32 v103, v141, v142
	v_cvt_pk_bf16_f32 v104, v143, v144
	v_cvt_pk_bf16_f32 v105, v145, v146
	s_waitcnt lgkmcnt(0)
	ds_read_b64_tr_b16 v[106:107], v68 offset:0
	ds_read_b64_tr_b16 v[108:109], v68 offset:0x400
	ds_read_b64_tr_b16 v[110:111], v68 offset:0x800
	ds_read_b64_tr_b16 v[112:113], v68 offset:0xc00
	ds_read_b64_tr_b16 v[114:115], v68 offset:0x200
	ds_read_b64_tr_b16 v[116:117], v68 offset:0x600
	ds_read_b64_tr_b16 v[118:119], v68 offset:0xa00
	ds_read_b64_tr_b16 v[120:121], v68 offset:0xe00
	s_waitcnt lgkmcnt(0)
	s_nop 0
	v_permlane32_swap_b32_e32 v98, v100
	v_permlane32_swap_b32_e32 v99, v101
	v_permlane32_swap_b32_e32 v102, v104
	v_permlane32_swap_b32_e32 v103, v105
	v_mfma_f32_32x32x16_bf16 v[0:15], v[98:101], v[106:109], v[0:15]
	v_mfma_f32_32x32x16_bf16 v[16:31], v[98:101], v[114:117], v[16:31]
	v_mfma_f32_32x32x16_bf16 v[0:15], v[102:105], v[110:113], v[0:15]
	v_mfma_f32_32x32x16_bf16 v[16:31], v[102:105], v[118:121], v[16:31]
	s_waitcnt vmcnt(8)
	ds_write_b128 v149, v[184:187]
	ds_write_b128 v150, v[188:191]
	ds_write_b128 v149, v[192:195] offset:2048
	ds_write_b128 v150, v[196:199] offset:2048
	v_cvt_pk_bf16_f32 v98, v56, v57
	v_cvt_pk_bf16_f32 v99, v60, v65
	v_cvt_pk_bf16_f32 v100, v69, v71
	v_cvt_pk_bf16_f32 v101, v75, v78
	v_cvt_pk_bf16_f32 v92, v72, v76
	v_cvt_pk_bf16_f32 v93, v79, v93
	v_cvt_pk_bf16_f32 v94, v94, v95
	v_cvt_pk_bf16_f32 v95, v96, v97
	s_waitcnt lgkmcnt(0)
	ds_read_b64_tr_b16 v[102:103], v68 offset:0
	ds_read_b64_tr_b16 v[104:105], v68 offset:0x400
	ds_read_b64_tr_b16 v[106:107], v68 offset:0x800
	ds_read_b64_tr_b16 v[108:109], v68 offset:0xc00
	ds_read_b64_tr_b16 v[110:111], v68 offset:0x200
	ds_read_b64_tr_b16 v[112:113], v68 offset:0x600
	ds_read_b64_tr_b16 v[114:115], v68 offset:0xa00
	ds_read_b64_tr_b16 v[116:117], v68 offset:0xe00
	s_waitcnt lgkmcnt(0)
	s_nop 0
	v_permlane32_swap_b32_e32 v98, v100
	v_permlane32_swap_b32_e32 v99, v101
	v_permlane32_swap_b32_e32 v92, v94
	v_permlane32_swap_b32_e32 v93, v95
	v_mfma_f32_32x32x16_bf16 v[0:15], v[98:101], v[102:105], v[0:15]
	v_mfma_f32_32x32x16_bf16 v[16:31], v[98:101], v[110:113], v[16:31]
	v_mfma_f32_32x32x16_bf16 v[0:15], v[92:95], v[106:109], v[0:15]
	v_mfma_f32_32x32x16_bf16 v[16:31], v[92:95], v[114:117], v[16:31]
	s_waitcnt vmcnt(4)
	ds_write_b128 v149, v[200:203]
	ds_write_b128 v150, v[204:207]
	ds_write_b128 v149, v[208:211] offset:2048
	ds_write_b128 v150, v[212:215] offset:2048
	v_cvt_pk_bf16_f32 v92, v35, v36
	v_cvt_pk_bf16_f32 v93, v37, v38
	v_cvt_pk_bf16_f32 v94, v42, v43
	v_cvt_pk_bf16_f32 v95, v45, v47
	v_cvt_pk_bf16_f32 v42, v44, v46
	v_cvt_pk_bf16_f32 v43, v48, v49
	v_cvt_pk_bf16_f32 v44, v50, v51
	v_cvt_pk_bf16_f32 v45, v147, v148
	s_waitcnt lgkmcnt(0)
	ds_read_b64_tr_b16 v[46:47], v68 offset:0
	ds_read_b64_tr_b16 v[48:49], v68 offset:0x400
	ds_read_b64_tr_b16 v[96:97], v68 offset:0x800
	ds_read_b64_tr_b16 v[98:99], v68 offset:0xc00
	ds_read_b64_tr_b16 v[100:101], v68 offset:0x200
	ds_read_b64_tr_b16 v[102:103], v68 offset:0x600
	ds_read_b64_tr_b16 v[104:105], v68 offset:0xa00
	ds_read_b64_tr_b16 v[106:107], v68 offset:0xe00
	s_waitcnt lgkmcnt(0)
	s_nop 0
	v_permlane32_swap_b32_e32 v92, v94
	v_permlane32_swap_b32_e32 v93, v95
	v_permlane32_swap_b32_e32 v42, v44
	v_permlane32_swap_b32_e32 v43, v45
	v_mfma_f32_32x32x16_bf16 v[0:15], v[92:95], v[46:49], v[0:15]
	v_mfma_f32_32x32x16_bf16 v[16:31], v[92:95], v[100:103], v[16:31]
	v_mfma_f32_32x32x16_bf16 v[0:15], v[42:45], v[96:99], v[0:15]
	v_mfma_f32_32x32x16_bf16 v[16:31], v[42:45], v[104:107], v[16:31]
	s_waitcnt vmcnt(0)
	ds_write_b128 v149, v[216:219]
	ds_write_b128 v150, v[220:223]
	ds_write_b128 v149, v[224:227] offset:2048
	ds_write_b128 v150, v[228:231] offset:2048
	v_cvt_pk_bf16_f32 v36, v52, v53
	v_cvt_pk_bf16_f32 v37, v54, v55
	v_cvt_pk_bf16_f32 v38, v58, v61
	v_cvt_pk_bf16_f32 v39, v63, v66
	v_cvt_pk_bf16_f32 v42, v59, v62
	v_cvt_pk_bf16_f32 v43, v64, v67
	v_cvt_pk_bf16_f32 v44, v70, v73
	v_cvt_pk_bf16_f32 v45, v74, v77
	s_waitcnt lgkmcnt(0)
	ds_read_b64_tr_b16 v[46:47], v68 offset:0
	ds_read_b64_tr_b16 v[48:49], v68 offset:0x400
	ds_read_b64_tr_b16 v[50:51], v68 offset:0x800
	ds_read_b64_tr_b16 v[52:53], v68 offset:0xc00
	ds_read_b64_tr_b16 v[54:55], v68 offset:0x200
	ds_read_b64_tr_b16 v[56:57], v68 offset:0x600
	ds_read_b64_tr_b16 v[58:59], v68 offset:0xa00
	ds_read_b64_tr_b16 v[60:61], v68 offset:0xe00
	s_waitcnt lgkmcnt(0)
	s_nop 0
	v_permlane32_swap_b32_e32 v36, v38
	v_permlane32_swap_b32_e32 v37, v39
	v_permlane32_swap_b32_e32 v42, v44
	v_permlane32_swap_b32_e32 v43, v45
	v_mfma_f32_32x32x16_bf16 v[0:15], v[36:39], v[46:49], v[0:15]
	v_mfma_f32_32x32x16_bf16 v[16:31], v[36:39], v[54:57], v[16:31]
	v_mfma_f32_32x32x16_bf16 v[0:15], v[42:45], v[50:53], v[0:15]
	v_mfma_f32_32x32x16_bf16 v[16:31], v[42:45], v[58:61], v[16:31]
	v_cmp_lt_u32_e32 vcc, 31, v87
	s_and_saveexec_b64 s[4:5], vcc
	s_xor_b64 s[4:5], exec, s[4:5]
	s_ashr_i32 s11, s10, 31
	s_lshl_b64 s[6:7], s[10:11], 15
	s_ashr_i32 s11, s79, 31
	s_add_u32 s6, s6, s79
	s_addc_u32 s7, s7, s11
	s_or_saveexec_b64 s[4:5], s[4:5]
	s_waitcnt lgkmcnt(14)
	v_add_f32_e32 v35, v40, v41
	v_mov_b64_e32 v[32:33], s[6:7]
	s_xor_b64 exec, exec, s[4:5]
	s_cbranch_execz .LBB0_82
; __device__ __forceinline__ void dil_wave_item(const bf16* __restrict__ qkv, bf16* __restrict__ odil, float* __restrict__ lse,
;                               int pat, int g  , int head, char* wl  , const int W) {
;     ...
;   if (hi == 0) lse[((size_t)pat * T + tbase + (i0 + r32) * dil) * 8 + head] = mx + __log2f(ls);
	v_log_f32_e32 v32, v35
	s_ashr_i32 s11, s10, 31
	s_ashr_i32 s66, s79, 31
	s_lshl_b64 s[6:7], s[10:11], 15
	s_add_u32 s6, s6, s79
	s_addc_u32 s7, s7, s66
	v_ashrrev_i32_e32 v87, 31, v86
	v_add_f32_e32 v34, v34, v32
	v_lshl_add_u64 v[32:33], s[6:7], 0, v[86:87]
	v_lshlrev_b64 v[32:33], 5, v[32:33]
	v_lshl_add_u64 v[32:33], s[72:73], 0, v[32:33]
	global_store_dword v[32:33], v34, off
	v_mov_b64_e32 v[32:33], s[6:7]
	s_branch .LBB0_82

; __device__ __forceinline__ void dil_wave_item(const bf16* __restrict__ qkv, bf16* __restrict__ odil, float* __restrict__ lse,
;                               int pat, int g  , int head, char* wl  , const int W) {
;     ...
;   const int dil = (pat == 0) ? 1 : (pat == 1 ? 4 : 16);
;   int seq0, slen, gl;
;   if (g < 256) { seq0 = 0; slen = 8192; gl = g; } else if (g < 512) { seq0 = 8192; slen = 8192; gl = g - 256; } else { seq0 = 16384; slen = 16384; gl = g - 512; }
;   const int L = slen / dil, tpr = L / 32, res = gl / tpr, i0 = (gl % tpr) * 32;
; __device__ __forceinline__ void attention_phase(const Params& p, int layer, const int W) {
;     ...
;   for (int rep = 0; rep < REP_DIL; ++rep)
;   for (int it = blockIdx.x; it < 3 * 1024; it += gridDim.x) {
;     dil_wave_item(qkv, odil, lse, it / 1024, it % 1024, wid, lds + wid * 4096, W);
.LBB0_294:
	s_and_b32 s98, s27, 0xffffff00
	s_and_b32 s99, s27, 7
	s_lshl_b32 s99, s99, 5
	s_or_b32 s98, s98, s99
	s_bfe_u32 s99, s27, 0x50003
	s_or_b32 s98, s98, s99
	s_ashr_i32 s6, s98, 31
	s_lshr_b32 s6, s6, 22
	s_add_i32 s6, s98, s6
	s_ashr_i32 s14, s6, 10
	s_and_b32 s6, s6, 0xfffffc00
	s_sub_i32 s15, s98, s6
	s_cmpk_lt_i32 s15, 0x100
	s_movk_i32 s7, 0x2000
	v_mbcnt_lo_u32_b32 v103, -1, 0
	v_mbcnt_hi_u32_b32 v103, -1, v103
	s_cbranch_scc1 .LBB0_300
	s_lshl_b32 s6, s14, 10
	s_sub_i32 s20, s98, s6
	s_cmpk_gt_u32 s15, 0x1ff
	s_mov_b64 s[6:7], -1
	s_cbranch_scc0 .LBB0_297
	s_add_i32 s15, s20, 0xfffffe00
	s_mov_b64 s[6:7], 0

; __device__ __forceinline__ void dil_wave_item(const bf16* __restrict__ qkv, bf16* __restrict__ odil, float* __restrict__ lse,
;                               int pat, int g  , int head, char* wl  , const int W) {
;     ...
;   const int dil = (pat == 0) ? 1 : (pat == 1 ? 4 : 16);
;   int seq0, slen, gl;
;   if (g < 256) { seq0 = 0; slen = 8192; gl = g; } else if (g < 512) { seq0 = 8192; slen = 8192; gl = g - 256; } else { seq0 = 16384; slen = 16384; gl = g - 512; }
;   const int L = slen / dil, tpr = L / 32, res = gl / tpr, i0 = (gl % tpr) * 32;
;   const int tbase = seq0 + res;
;   bf16x8 qr[4];
;   { const bf16* qp = qkv + (size_t)(tbase + (i0 + r32) * dil) * LDQ + 1536 + head * 64 + hi * 8;
; #pragma unroll
;     for (int d0 = 0; d0 < 4; ++d0) qr[d0] = *reinterpret_cast<const bf16x8*>(qp + d0 * 16); }
;   f32x16 sc[5];
; #pragma unroll
;   for (int kb = 0; kb < 5; ++kb) {
;     int kc = i0 - 64 + kb * 32 + r32; kc = min(max(kc, 0), L - 1);
;     const bf16* kp = qkv + (size_t)(tbase + kc * dil) * LDQ + 2048 + head * 64 + hi * 8;
;     f32x16 a = {};
; #pragma unroll
;     for (int d0 = 0; d0 < 4; ++d0) {
;       bf16x8 kf = *reinterpret_cast<const bf16x8*>(kp + d0 * 16);
;       a = __builtin_amdgcn_mfma_f32_32x32x16_bf16(kf, qr[d0], a, 0, 0, 0);
;     }
;     sc[kb] = a;
;   }
.LBB0_301:
	s_add_i32 s8, s98, 0x3ff
	s_and_b32 s9, s98, 0xfffffc00
	s_cmpk_eq_i32 s9, 0x400
	s_cselect_b32 s9, 2, 4
	s_cmpk_gt_u32 s8, 0x7fe
	s_cselect_b32 s40, s9, 0
	s_lshr_b32 s20, s7, s40
	s_lshr_b32 s7, s20, 5
	s_sext_i32_i16 s9, s7
	v_cvt_f32_i32_e32 v1, s9
	s_sext_i32_i16 s8, s15
	v_cvt_f32_i32_e32 v0, s8
	s_xor_b32 s21, s8, s9
	v_rcp_iflag_f32_e32 v2, v1
	s_ashr_i32 s21, s21, 30
	s_or_b32 s21, s21, 1
	v_and_b32_e32 v102, 31, v103
	v_mul_f32_e32 v2, v0, v2
	v_trunc_f32_e32 v2, v2
	v_fma_f32 v0, -v2, v1, v0
	v_cvt_i32_f32_e32 v2, v2
	v_cmp_ge_f32_e64 s[8:9], |v0|, |v1|
	s_and_b64 s[8:9], s[8:9], exec
	s_cselect_b32 s8, s21, 0
	v_readfirstlane_b32 s9, v2
	s_add_i32 s8, s9, s8
	s_sext_i32_i16 s9, s8
	s_mul_i32 s8, s8, s7
	s_sub_i32 s7, s15, s8
	s_sext_i32_i16 s7, s7
	s_lshl_b32 s41, s7, 5
	v_or_b32_e32 v104, s41, v102
	s_add_i32 s42, s6, s9
	v_lshlrev_b32_e32 v98, s40, v104
	v_bfe_u32 v105, v103, 5, 1
	v_add_u32_e32 v0, s42, v98
	v_mad_i64_i32 v[0:1], s[6:7], v0, s24, v[92:93]
	v_lshlrev_b32_e32 v94, 4, v105
	v_lshl_add_u64 v[4:5], v[0:1], 0, v[94:95]
	v_subrev_u32_e32 v10, 64, v104
	global_load_dwordx4 v[0:3], v[4:5], off offset:3072
	global_load_dwordx4 v[88:91], v[4:5], off offset:3104
	global_load_dwordx4 v[84:87], v[4:5], off offset:3136
	global_load_dwordx4 v[80:83], v[4:5], off offset:3168
	s_add_i32 s15, s20, -1
	v_max_i32_e32 v4, 0, v10
	v_min_u32_e32 v4, s15, v4
	v_lshlrev_b32_e32 v4, s40, v4
	v_add_u32_e32 v4, s42, v4
	v_mad_i64_i32 v[4:5], s[6:7], v4, s24, v[96:97]
	v_lshl_add_u64 v[4:5], v[4:5], 0, s[74:75]
	v_lshl_add_u64 v[4:5], v[4:5], 0, v[94:95]
	v_lshl_add_u64 v[8:9], v[4:5], 0, s[10:11]
	v_add_co_u32_e32 v4, vcc, s25, v4
	v_and_b32_e32 v99, 63, v103
	s_nop 0
	v_addc_co_u32_e32 v5, vcc, 0, v5, vcc
	global_load_dwordx4 v[4:7], v[4:5], off
	s_waitcnt vmcnt(0)
	v_mfma_f32_32x32x16_bf16 v[64:79], v[4:7], v[0:3], 0
	global_load_dwordx4 v[4:7], v[8:9], off offset:32
	s_waitcnt vmcnt(0)
	v_mfma_f32_32x32x16_bf16 v[64:79], v[4:7], v[88:91], v[64:79]
	global_load_dwordx4 v[4:7], v[8:9], off offset:64
	s_waitcnt vmcnt(0)
	v_mfma_f32_32x32x16_bf16 v[64:79], v[4:7], v[84:87], v[64:79]
	global_load_dwordx4 v[4:7], v[8:9], off offset:96
	s_waitcnt vmcnt(0)
	v_mfma_f32_32x32x16_bf16 v[64:79], v[4:7], v[80:83], v[64:79]
	v_max_i32_e32 v4, 0xffffffe0, v10
	v_add_u32_e32 v4, 32, v4
	v_min_u32_e32 v4, s15, v4
	v_lshlrev_b32_e32 v4, s40, v4
	v_add_u32_e32 v4, s42, v4
	v_mad_i64_i32 v[4:5], s[6:7], v4, s24, v[96:97]
	v_lshl_add_u64 v[4:5], v[4:5], 0, s[74:75]
	v_lshl_add_u64 v[4:5], v[4:5], 0, v[94:95]
	v_lshl_add_u64 v[8:9], v[4:5], 0, s[10:11]
	v_add_co_u32_e32 v4, vcc, s25, v4
	s_nop 1
	v_mul_f32_e32 v64, 0x3e38aa3b, v64
	v_addc_co_u32_e32 v5, vcc, 0, v5, vcc
	global_load_dwordx4 v[4:7], v[4:5], off
	v_mul_f32_e32 v65, 0x3e38aa3b, v65
	v_mul_f32_e32 v66, 0x3e38aa3b, v66
	v_mul_f32_e32 v67, 0x3e38aa3b, v67
	s_waitcnt vmcnt(0)
	v_mfma_f32_32x32x16_bf16 v[48:63], v[4:7], v[0:3], 0
	global_load_dwordx4 v[4:7], v[8:9], off offset:32
	s_waitcnt vmcnt(0)
	v_mfma_f32_32x32x16_bf16 v[48:63], v[4:7], v[88:91], v[48:63]
	global_load_dwordx4 v[4:7], v[8:9], off offset:64
	s_waitcnt vmcnt(0)
	v_mfma_f32_32x32x16_bf16 v[48:63], v[4:7], v[84:87], v[48:63]
	global_load_dwordx4 v[4:7], v[8:9], off offset:96
	s_waitcnt vmcnt(0)
	v_mfma_f32_32x32x16_bf16 v[48:63], v[4:7], v[80:83], v[48:63]
	v_max_i32_e32 v4, 0xffffffc0, v10
	v_add_u32_e32 v4, 64, v4
	v_min_u32_e32 v4, s15, v4
	v_lshlrev_b32_e32 v4, s40, v4
	v_add_u32_e32 v4, s42, v4
	v_mad_i64_i32 v[4:5], s[6:7], v4, s24, v[96:97]
	v_lshl_add_u64 v[4:5], v[4:5], 0, s[74:75]
	v_lshl_add_u64 v[4:5], v[4:5], 0, v[94:95]
	v_lshl_add_u64 v[8:9], v[4:5], 0, s[10:11]
	v_add_co_u32_e32 v4, vcc, s25, v4
	s_nop 1
	v_mul_f32_e32 v48, 0x3e38aa3b, v48
	v_addc_co_u32_e32 v5, vcc, 0, v5, vcc
	global_load_dwordx4 v[4:7], v[4:5], off
	v_mul_f32_e32 v49, 0x3e38aa3b, v49
	v_mul_f32_e32 v50, 0x3e38aa3b, v50
	s_waitcnt vmcnt(0)
	v_mfma_f32_32x32x16_bf16 v[32:47], v[4:7], v[0:3], 0
	global_load_dwordx4 v[4:7], v[8:9], off offset:32
	s_waitcnt vmcnt(0)
	v_mfma_f32_32x32x16_bf16 v[32:47], v[4:7], v[88:91], v[32:47]
	global_load_dwordx4 v[4:7], v[8:9], off offset:64
	s_waitcnt vmcnt(0)
	v_mfma_f32_32x32x16_bf16 v[32:47], v[4:7], v[84:87], v[32:47]
	global_load_dwordx4 v[4:7], v[8:9], off offset:96
	s_waitcnt vmcnt(0)
	v_mfma_f32_32x32x16_bf16 v[32:47], v[4:7], v[80:83], v[32:47]
	v_max_i32_e32 v4, 0xffffffa0, v10
	v_add_u32_e32 v4, 0x60, v4
	v_min_u32_e32 v4, s15, v4
	v_lshlrev_b32_e32 v4, s40, v4
	v_add_u32_e32 v4, s42, v4
	v_mad_i64_i32 v[4:5], s[6:7], v4, s24, v[96:97]
	v_lshl_add_u64 v[4:5], v[4:5], 0, s[74:75]
	v_lshl_add_u64 v[4:5], v[4:5], 0, v[94:95]
	v_lshl_add_u64 v[8:9], v[4:5], 0, s[10:11]
	v_add_co_u32_e32 v4, vcc, s25, v4
	s_nop 1
	v_mul_f32_e32 v32, 0x3e38aa3b, v32
	v_addc_co_u32_e32 v5, vcc, 0, v5, vcc
	global_load_dwordx4 v[4:7], v[4:5], off
	v_mul_f32_e32 v33, 0x3e38aa3b, v33
	v_mul_f32_e32 v34, 0x3e38aa3b, v34
	s_waitcnt vmcnt(0)
	v_mfma_f32_32x32x16_bf16 v[16:31], v[4:7], v[0:3], 0
	global_load_dwordx4 v[4:7], v[8:9], off offset:32
	s_waitcnt vmcnt(0)
	v_mfma_f32_32x32x16_bf16 v[16:31], v[4:7], v[88:91], v[16:31]
	global_load_dwordx4 v[4:7], v[8:9], off offset:64
	s_waitcnt vmcnt(0)
	v_mfma_f32_32x32x16_bf16 v[16:31], v[4:7], v[84:87], v[16:31]
	global_load_dwordx4 v[4:7], v[8:9], off offset:96
	s_waitcnt vmcnt(0)
; __device__ __forceinline__ int crow(int r, int hi) { return (r & 3) + 8 * (r >> 2) + 4 * hi; }
; __device__ __forceinline__ void dil_wave_item(const bf16* __restrict__ qkv, bf16* __restrict__ odil, float* __restrict__ lse,
;                               int pat, int g  , int head, char* wl  , const int W) {
;     ...
;   for (int kb = 0; kb < 5; ++kb) {
;     int kc = i0 - 64 + kb * 32 + r32; kc = min(max(kc, 0), L - 1);
;     const bf16* kp = qkv + (size_t)(tbase + kc * dil) * LDQ + 2048 + head * 64 + hi * 8;
;     f32x16 a = {};
; #pragma unroll
;     for (int d0 = 0; d0 < 4; ++d0) {
;       bf16x8 kf = *reinterpret_cast<const bf16x8*>(kp + d0 * 16);
;       a = __builtin_amdgcn_mfma_f32_32x32x16_bf16(kf, qr[d0], a, 0, 0, 0);
;     }
;     sc[kb] = a;
;   }
;   float mx = -1e30f;
; #pragma unroll
;   for (int kb = 0; kb < 5; ++kb)
; #pragma unroll
;     for (int r = 0; r < 16; ++r) {
;       const int rel = kb * 32 - 64 + crow(r, hi) - r32;
;       const int kc = i0 + r32 + rel;
;       const bool ok = (rel >= -64) && (rel <= 64) && (kc >= 0) && (kc < L);
;       const float s = ok ? sc[kb][r] * AC : -1e30f;
;       sc[kb][r] = s; mx = fmaxf(mx, s);
;     }
	v_mfma_f32_32x32x16_bf16 v[16:31], v[4:7], v[80:83], v[16:31]
	v_max_i32_e32 v4, 0xffffff80, v10
	v_add_u32_e32 v4, 0x80, v4
	v_min_u32_e32 v4, s15, v4
	v_lshlrev_b32_e32 v4, s40, v4
	v_add_u32_e32 v4, s42, v4
	v_mad_i64_i32 v[4:5], s[6:7], v4, s24, v[96:97]
	v_lshl_add_u64 v[4:5], v[4:5], 0, s[74:75]
	v_lshl_add_u64 v[4:5], v[4:5], 0, v[94:95]
	v_lshl_add_u64 v[110:111], v[4:5], 0, s[10:11]
	v_add_co_u32_e32 v4, vcc, s25, v4
	global_load_dwordx4 v[106:109], v[110:111], off offset:32
	s_nop 0
	v_addc_co_u32_e32 v5, vcc, 0, v5, vcc
	global_load_dwordx4 v[4:7], v[4:5], off
	v_mul_f32_e32 v16, 0x3e38aa3b, v16
	s_waitcnt vmcnt(0)
	v_mfma_f32_32x32x16_bf16 v[0:15], v[4:7], v[0:3], 0
	v_mfma_f32_32x32x16_bf16 v[0:15], v[106:109], v[88:91], v[0:15]
	global_load_dwordx4 v[88:91], v[110:111], off offset:64
	s_waitcnt vmcnt(0)
	v_mfma_f32_32x32x16_bf16 v[0:15], v[88:91], v[84:87], v[0:15]
	global_load_dwordx4 v[84:87], v[110:111], off offset:96
	s_waitcnt vmcnt(0)
	v_mfma_f32_32x32x16_bf16 v[0:15], v[84:87], v[80:83], v[0:15]
	v_lshlrev_b32_e32 v80, 2, v105
	v_sub_u32_e32 v81, v80, v102
	v_add_u32_e32 v82, v104, v81
	v_subrev_u32_e32 v83, 64, v82
	v_cmp_gt_u32_e32 vcc, s26, v81
	v_cmp_gt_u32_e64 s[6:7], s20, v83
	s_and_b64 vcc, vcc, s[6:7]
	v_subrev_u32_e32 v83, 63, v82
	v_add_u32_e32 v86, 1, v81
	v_cndmask_b32_e32 v64, v101, v64, vcc
	v_cmp_gt_u32_e32 vcc, s26, v86
	v_cmp_gt_u32_e64 s[6:7], s20, v83
	s_and_b64 vcc, vcc, s[6:7]
	v_cndmask_b32_e32 v65, v101, v65, vcc
	s_mov_b32 s6, 0xf149f2ca
	v_subrev_u32_e32 v83, 62, v82
	v_add_u32_e32 v87, 2, v81
	v_max3_f32 v84, v64, s6, v65
	v_cmp_gt_u32_e32 vcc, s26, v87
	v_cmp_gt_u32_e64 s[6:7], s20, v83
	s_and_b64 vcc, vcc, s[6:7]
	v_subrev_u32_e32 v83, 61, v82
	v_add_u32_e32 v88, 3, v81
	v_cndmask_b32_e32 v66, v101, v66, vcc
	v_cmp_gt_u32_e32 vcc, s26, v88
	v_cmp_gt_u32_e64 s[6:7], s20, v83
	s_and_b64 vcc, vcc, s[6:7]
	v_cndmask_b32_e32 v83, v101, v67, vcc
	v_subrev_u32_e32 v67, 56, v82
	v_add_u32_e32 v89, 8, v81
	v_cmp_gt_u32_e32 vcc, s26, v89
	v_cmp_gt_u32_e64 s[6:7], s20, v67
	s_and_b64 vcc, vcc, s[6:7]
	v_mul_f32_e32 v67, 0x3e38aa3b, v68
	v_subrev_u32_e32 v68, 55, v82
	v_add_u32_e32 v90, 9, v81
	v_cndmask_b32_e32 v67, v101, v67, vcc
	v_cmp_gt_u32_e32 vcc, s26, v90
	v_cmp_gt_u32_e64 s[6:7], s20, v68
	s_and_b64 vcc, vcc, s[6:7]
	v_mul_f32_e32 v68, 0x3e38aa3b, v69
	v_subrev_u32_e32 v69, 54, v82
	v_add_u32_e32 v91, 10, v81
	v_cndmask_b32_e32 v68, v101, v68, vcc
	v_cmp_gt_u32_e32 vcc, s26, v91
	v_cmp_gt_u32_e64 s[6:7], s20, v69
	s_and_b64 vcc, vcc, s[6:7]
	v_mul_f32_e32 v69, 0x3e38aa3b, v70
	v_subrev_u32_e32 v70, 53, v82
	v_add_u32_e32 v105, 11, v81
	v_cndmask_b32_e32 v69, v101, v69, vcc
	v_cmp_gt_u32_e32 vcc, s26, v105
	v_cmp_gt_u32_e64 s[6:7], s20, v70
	s_and_b64 vcc, vcc, s[6:7]
	v_mul_f32_e32 v70, 0x3e38aa3b, v71
	v_cndmask_b32_e32 v71, v101, v70, vcc
	v_subrev_u32_e32 v70, 48, v82
	v_add_u32_e32 v106, 16, v81
	v_cmp_gt_u32_e32 vcc, s26, v106
	v_cmp_gt_u32_e64 s[6:7], s20, v70
	s_and_b64 vcc, vcc, s[6:7]
	v_mul_f32_e32 v70, 0x3e38aa3b, v72
	v_subrev_u32_e32 v72, 47, v82
	v_add_u32_e32 v107, 17, v81
	v_cndmask_b32_e32 v70, v101, v70, vcc
	v_cmp_gt_u32_e32 vcc, s26, v107
	v_cmp_gt_u32_e64 s[6:7], s20, v72
	s_and_b64 vcc, vcc, s[6:7]
	v_mul_f32_e32 v72, 0x3e38aa3b, v73
	v_subrev_u32_e32 v73, 46, v82
	v_add_u32_e32 v108, 18, v81
	v_cndmask_b32_e32 v72, v101, v72, vcc
	v_cmp_gt_u32_e32 vcc, s26, v108
	v_cmp_gt_u32_e64 s[6:7], s20, v73
	s_and_b64 vcc, vcc, s[6:7]
	v_mul_f32_e32 v73, 0x3e38aa3b, v74
	v_subrev_u32_e32 v74, 45, v82
	v_add_u32_e32 v109, 19, v81
	v_cndmask_b32_e32 v73, v101, v73, vcc
	v_cmp_gt_u32_e32 vcc, s26, v109
	v_cmp_gt_u32_e64 s[6:7], s20, v74
	s_and_b64 vcc, vcc, s[6:7]
	v_mul_f32_e32 v74, 0x3e38aa3b, v75
	v_cndmask_b32_e32 v75, v101, v74, vcc
	v_subrev_u32_e32 v74, 40, v82
	v_add_u32_e32 v110, 24, v81
	v_cmp_gt_u32_e32 vcc, s26, v110
	v_cmp_gt_u32_e64 s[6:7], s20, v74
	s_and_b64 vcc, vcc, s[6:7]
	v_mul_f32_e32 v74, 0x3e38aa3b, v76
	v_subrev_u32_e32 v76, 39, v82
	v_add_u32_e32 v111, 25, v81
	v_cndmask_b32_e32 v74, v101, v74, vcc
	v_cmp_gt_u32_e32 vcc, s26, v111
	v_cmp_gt_u32_e64 s[6:7], s20, v76
	v_max3_f32 v84, v84, v66, v83
	s_and_b64 vcc, vcc, s[6:7]
	v_mul_f32_e32 v76, 0x3e38aa3b, v77
	v_subrev_u32_e32 v77, 38, v82
	v_add_u32_e32 v112, 26, v81
	v_max3_f32 v84, v84, v67, v68
	v_cndmask_b32_e32 v76, v101, v76, vcc
	v_cmp_gt_u32_e32 vcc, s26, v112
	v_cmp_gt_u32_e64 s[6:7], s20, v77
	v_max3_f32 v84, v84, v69, v71
	s_and_b64 vcc, vcc, s[6:7]
	v_mul_f32_e32 v77, 0x3e38aa3b, v78
	v_subrev_u32_e32 v78, 37, v82
	v_add_u32_e32 v113, 27, v81
	v_max3_f32 v84, v84, v70, v72
	v_cndmask_b32_e32 v77, v101, v77, vcc
	v_cmp_gt_u32_e32 vcc, s26, v113
	v_cmp_gt_u32_e64 s[6:7], s20, v78
	v_max3_f32 v84, v84, v73, v75
	s_and_b64 vcc, vcc, s[6:7]
	v_mul_f32_e32 v78, 0x3e38aa3b, v79
	v_max3_f32 v84, v84, v74, v76
	v_cndmask_b32_e32 v78, v101, v78, vcc
	v_max3_f32 v79, v84, v77, v78
	v_subrev_u32_e32 v84, 32, v82
	v_cmp_gt_u32_e32 vcc, s20, v84
	v_subrev_u32_e32 v84, 31, v82
	v_mul_f32_e32 v0, 0x3e38aa3b, v0
	v_cndmask_b32_e32 v48, v101, v48, vcc
	v_cmp_gt_u32_e32 vcc, s20, v84
	v_mul_f32_e32 v1, 0x3e38aa3b, v1
	v_mul_f32_e32 v2, 0x3e38aa3b, v2
	v_cndmask_b32_e32 v49, v101, v49, vcc
	v_max3_f32 v85, v79, v48, v49
	v_subrev_u32_e32 v79, 30, v82
	v_cmp_gt_u32_e32 vcc, s20, v79
	v_mul_f32_e32 v3, 0x3e38aa3b, v3
	v_mul_f32_e32 v4, 0x3e38aa3b, v4
	v_cndmask_b32_e32 v79, v101, v50, vcc
	v_subrev_u32_e32 v50, 29, v82
	v_cmp_gt_u32_e32 vcc, s20, v50
	v_mul_f32_e32 v50, 0x3e38aa3b, v51
	v_subrev_u32_e32 v51, 23, v82
	v_cndmask_b32_e32 v84, v101, v50, vcc
	v_subrev_u32_e32 v50, 24, v82
	v_cmp_gt_u32_e32 vcc, s20, v50
; __device__ __forceinline__ int crow(int r, int hi) { return (r & 3) + 8 * (r >> 2) + 4 * hi; }
; __device__ __forceinline__ void dil_wave_item(const bf16* __restrict__ qkv, bf16* __restrict__ odil, float* __restrict__ lse,
;                               int pat, int g  , int head, char* wl  , const int W) {
;     ...
;   float mx = -1e30f;
; #pragma unroll
;   for (int kb = 0; kb < 5; ++kb)
; #pragma unroll
;     for (int r = 0; r < 16; ++r) {
;       const int rel = kb * 32 - 64 + crow(r, hi) - r32;
;       const int kc = i0 + r32 + rel;
;       const bool ok = (rel >= -64) && (rel <= 64) && (kc >= 0) && (kc < L);
;       const float s = ok ? sc[kb][r] * AC : -1e30f;
;       sc[kb][r] = s; mx = fmaxf(mx, s);
;     }
	v_mul_f32_e32 v50, 0x3e38aa3b, v52
	v_max3_f32 v85, v85, v79, v84
	v_cndmask_b32_e32 v50, v101, v50, vcc
	v_cmp_gt_u32_e32 vcc, s20, v51
	v_mul_f32_e32 v51, 0x3e38aa3b, v53
	v_subrev_u32_e32 v53, 22, v82
	v_cndmask_b32_e32 v51, v101, v51, vcc
	v_cmp_gt_u32_e32 vcc, s20, v53
	v_mul_f32_e32 v53, 0x3e38aa3b, v54
	v_subrev_u32_e32 v54, 21, v82
	v_cndmask_b32_e32 v53, v101, v53, vcc
	v_cmp_gt_u32_e32 vcc, s20, v54
	v_mul_f32_e32 v54, 0x3e38aa3b, v55
	v_max3_f32 v52, v85, v50, v51
	v_cndmask_b32_e32 v85, v101, v54, vcc
	v_max3_f32 v55, v52, v53, v85
	v_add_u32_e32 v52, -16, v82
	v_cmp_gt_u32_e32 vcc, s20, v52
	v_mul_f32_e32 v52, 0x3e38aa3b, v56
	v_add_u32_e32 v54, -15, v82
	v_cndmask_b32_e32 v52, v101, v52, vcc
	v_cmp_gt_u32_e32 vcc, s20, v54
	v_mul_f32_e32 v54, 0x3e38aa3b, v57
	v_add_u32_e32 v56, -14, v82
	v_cndmask_b32_e32 v54, v101, v54, vcc
	v_cmp_gt_u32_e32 vcc, s20, v56
	v_mul_f32_e32 v56, 0x3e38aa3b, v58
	v_add_u32_e32 v58, -7, v82
	v_cndmask_b32_e32 v57, v101, v56, vcc
	v_add_u32_e32 v56, -13, v82
	v_cmp_gt_u32_e32 vcc, s20, v56
	v_mul_f32_e32 v56, 0x3e38aa3b, v59
	v_max3_f32 v55, v55, v52, v54
	v_cndmask_b32_e32 v59, v101, v56, vcc
	v_add_u32_e32 v56, -8, v82
	v_cmp_gt_u32_e32 vcc, s20, v56
	v_mul_f32_e32 v56, 0x3e38aa3b, v60
	v_add_u32_e32 v60, -6, v82
	v_cndmask_b32_e32 v56, v101, v56, vcc
	v_cmp_gt_u32_e32 vcc, s20, v58
	v_mul_f32_e32 v58, 0x3e38aa3b, v61
	v_add_u32_e32 v61, -5, v82
	v_cndmask_b32_e32 v58, v101, v58, vcc
	v_cmp_gt_u32_e32 vcc, s20, v60
	v_mul_f32_e32 v60, 0x3e38aa3b, v62
	v_add_u32_e32 v62, v104, v86
	v_cndmask_b32_e32 v60, v101, v60, vcc
	v_cmp_gt_u32_e32 vcc, s20, v61
	v_mul_f32_e32 v61, 0x3e38aa3b, v63
	v_max3_f32 v55, v55, v57, v59
	v_cndmask_b32_e32 v61, v101, v61, vcc
	v_cmp_gt_u32_e32 vcc, s20, v82
	v_max3_f32 v55, v55, v56, v58
	v_max3_f32 v55, v55, v60, v61
	v_cndmask_b32_e32 v32, v101, v32, vcc
	v_cmp_gt_u32_e32 vcc, s20, v62
	v_add_u32_e32 v62, v104, v87
	v_mul_f32_e32 v5, 0x3e38aa3b, v5
	v_cndmask_b32_e32 v33, v101, v33, vcc
	v_cmp_gt_u32_e32 vcc, s20, v62
	v_max3_f32 v55, v55, v32, v33
	v_mul_f32_e32 v6, 0x3e38aa3b, v6
	v_cndmask_b32_e32 v62, v101, v34, vcc
	v_add_u32_e32 v34, v104, v88
	v_cmp_gt_u32_e32 vcc, s20, v34
	v_mul_f32_e32 v34, 0x3e38aa3b, v35
	v_add_u32_e32 v35, v104, v89
	v_cndmask_b32_e32 v63, v101, v34, vcc
	v_cmp_gt_u32_e32 vcc, s20, v35
	v_mul_f32_e32 v35, 0x3e38aa3b, v36
	v_add_u32_e32 v36, v104, v90
	v_cndmask_b32_e32 v35, v101, v35, vcc
	v_cmp_gt_u32_e32 vcc, s20, v36
	v_mul_f32_e32 v36, 0x3e38aa3b, v37
	v_add_u32_e32 v37, v104, v91
	v_cndmask_b32_e32 v36, v101, v36, vcc
	v_cmp_gt_u32_e32 vcc, s20, v37
	v_mul_f32_e32 v37, 0x3e38aa3b, v38
	v_max3_f32 v34, v55, v62, v63
	v_cndmask_b32_e32 v88, v101, v37, vcc
	v_add_u32_e32 v37, v104, v105
	v_cmp_gt_u32_e32 vcc, s20, v37
	v_mul_f32_e32 v37, 0x3e38aa3b, v39
	v_max3_f32 v34, v34, v35, v36
	v_cndmask_b32_e32 v105, v101, v37, vcc
	v_add_u32_e32 v37, v104, v106
	v_cmp_gt_u32_e32 vcc, s20, v37
	v_mul_f32_e32 v37, 0x3e38aa3b, v40
	v_max3_f32 v34, v34, v88, v105
	v_cndmask_b32_e32 v87, v101, v37, vcc
	v_add_u32_e32 v37, v104, v107
	v_cmp_gt_u32_e32 vcc, s20, v37
	v_mul_f32_e32 v37, 0x3e38aa3b, v41
	v_mul_f32_e32 v7, 0x3e38aa3b, v7
	v_cndmask_b32_e32 v90, v101, v37, vcc
	v_add_u32_e32 v37, v104, v108
	v_cmp_gt_u32_e32 vcc, s20, v37
	v_mul_f32_e32 v37, 0x3e38aa3b, v42
	v_max3_f32 v34, v34, v87, v90
	v_cndmask_b32_e32 v108, v101, v37, vcc
	v_add_u32_e32 v37, v104, v109
	v_cmp_gt_u32_e32 vcc, s20, v37
	v_mul_f32_e32 v37, 0x3e38aa3b, v43
	v_mul_f32_e32 v8, 0x3e38aa3b, v8
	v_cndmask_b32_e32 v109, v101, v37, vcc
	v_add_u32_e32 v37, v104, v110
	v_cmp_gt_u32_e32 vcc, s20, v37
	v_mul_f32_e32 v37, 0x3e38aa3b, v44
	v_max3_f32 v34, v34, v108, v109
	v_cndmask_b32_e32 v107, v101, v37, vcc
	v_add_u32_e32 v37, v104, v111
	v_cmp_gt_u32_e32 vcc, s20, v37
	v_mul_f32_e32 v37, 0x3e38aa3b, v45
	v_mul_f32_e32 v9, 0x3e38aa3b, v9
	v_cndmask_b32_e32 v45, v101, v37, vcc
	v_add_u32_e32 v37, v104, v112
	v_cmp_gt_u32_e32 vcc, s20, v37
	v_mul_f32_e32 v37, 0x3e38aa3b, v46
	v_max3_f32 v34, v34, v107, v45
	v_cndmask_b32_e32 v110, v101, v37, vcc
	v_add_u32_e32 v37, v104, v113
	v_cmp_gt_u32_e32 vcc, s20, v37
	v_mul_f32_e32 v37, 0x3e38aa3b, v47
	v_mul_f32_e32 v10, 0x3e38aa3b, v10
	v_cndmask_b32_e32 v111, v101, v37, vcc
	v_add_u32_e32 v37, 32, v82
	v_cmp_gt_u32_e32 vcc, s20, v37
	v_max3_f32 v34, v34, v110, v111
	v_mul_f32_e32 v11, 0x3e38aa3b, v11
	v_cndmask_b32_e32 v46, v101, v16, vcc
	v_add_u32_e32 v16, 33, v82
	v_cmp_gt_u32_e32 vcc, s20, v16
	v_mul_f32_e32 v16, 0x3e38aa3b, v17
	v_add_u32_e32 v17, 34, v82
	v_cndmask_b32_e32 v104, v101, v16, vcc
	v_cmp_gt_u32_e32 vcc, s20, v17
	v_mul_f32_e32 v17, 0x3e38aa3b, v18
	v_add_u32_e32 v18, 0x80, v81
	v_cndmask_b32_e32 v113, v101, v17, vcc
	v_add_u32_e32 v17, 35, v82
	v_cmp_gt_u32_e32 vcc, s20, v17
	v_mul_f32_e32 v17, 0x3e38aa3b, v19
	v_max3_f32 v16, v34, v46, v104
	v_cndmask_b32_e32 v115, v101, v17, vcc
	v_add_u32_e32 v17, 40, v82
	v_cmp_gt_u32_e32 vcc, s20, v17
	v_mul_f32_e32 v17, 0x3e38aa3b, v20
	v_max3_f32 v16, v16, v113, v115
	v_cndmask_b32_e32 v112, v101, v17, vcc
	v_add_u32_e32 v17, 41, v82
	v_cmp_gt_u32_e32 vcc, s20, v17
	v_mul_f32_e32 v17, 0x3e38aa3b, v21
	v_mul_f32_e32 v12, 0x3e38aa3b, v12
	v_cndmask_b32_e32 v114, v101, v17, vcc
	v_add_u32_e32 v17, 42, v82
	v_cmp_gt_u32_e32 vcc, s20, v17
	v_mul_f32_e32 v17, 0x3e38aa3b, v22
	v_max3_f32 v16, v16, v112, v114
	v_cndmask_b32_e32 v117, v101, v17, vcc
	v_add_u32_e32 v17, 43, v82
	v_cmp_gt_u32_e32 vcc, s20, v17
	v_mul_f32_e32 v17, 0x3e38aa3b, v23
	v_mul_f32_e32 v13, 0x3e38aa3b, v13
	v_cndmask_b32_e32 v119, v101, v17, vcc
	v_add_u32_e32 v17, 48, v82
	v_cmp_gt_u32_e32 vcc, s20, v17
; __device__ __forceinline__ float shfl_idx(float v, int srclane) { return __int_as_float(__builtin_amdgcn_ds_bpermute(srclane << 2, __float_as_int(v))); }
; __device__ __forceinline__ int crow(int r, int hi) { return (r & 3) + 8 * (r >> 2) + 4 * hi; }
; __device__ __forceinline__ void dil_wave_item(const bf16* __restrict__ qkv, bf16* __restrict__ odil, float* __restrict__ lse,
;                               int pat, int g  , int head, char* wl  , const int W) {
;     ...
;   float mx = -1e30f;
; #pragma unroll
;   for (int kb = 0; kb < 5; ++kb)
; #pragma unroll
;     for (int r = 0; r < 16; ++r) {
;       const int rel = kb * 32 - 64 + crow(r, hi) - r32;
;       const int kc = i0 + r32 + rel;
;       const bool ok = (rel >= -64) && (rel <= 64) && (kc >= 0) && (kc < L);
;       const float s = ok ? sc[kb][r] * AC : -1e30f;
;       sc[kb][r] = s; mx = fmaxf(mx, s);
;     }
;   mx = fmaxf(mx, shfl_idx(mx, lane ^ 32));
	v_mul_f32_e32 v17, 0x3e38aa3b, v24
	v_max3_f32 v16, v16, v117, v119
	v_cndmask_b32_e32 v116, v101, v17, vcc
	v_add_u32_e32 v17, 49, v82
	v_cmp_gt_u32_e32 vcc, s20, v17
	v_mul_f32_e32 v17, 0x3e38aa3b, v25
	v_mul_f32_e32 v14, 0x3e38aa3b, v14
	v_cndmask_b32_e32 v118, v101, v17, vcc
	v_add_u32_e32 v17, 50, v82
	v_cmp_gt_u32_e32 vcc, s20, v17
	v_mul_f32_e32 v17, 0x3e38aa3b, v26
	v_max3_f32 v16, v16, v116, v118
	v_cndmask_b32_e32 v121, v101, v17, vcc
	v_add_u32_e32 v17, 51, v82
	v_cmp_gt_u32_e32 vcc, s20, v17
	v_mul_f32_e32 v17, 0x3e38aa3b, v27
	v_mul_f32_e32 v15, 0x3e38aa3b, v15
	v_cndmask_b32_e32 v123, v101, v17, vcc
	v_add_u32_e32 v17, 56, v82
	v_cmp_gt_u32_e32 vcc, s20, v17
	v_mul_f32_e32 v17, 0x3e38aa3b, v28
	v_max3_f32 v16, v16, v121, v123
	v_cndmask_b32_e32 v120, v101, v17, vcc
	v_add_u32_e32 v17, 57, v82
	v_cmp_gt_u32_e32 vcc, s20, v17
	v_mul_f32_e32 v17, 0x3e38aa3b, v29
	s_nop 0
	v_cndmask_b32_e32 v122, v101, v17, vcc
	v_add_u32_e32 v17, 58, v82
	v_cmp_gt_u32_e32 vcc, s20, v17
	v_mul_f32_e32 v17, 0x3e38aa3b, v30
	v_max3_f32 v16, v16, v120, v122
	v_cndmask_b32_e32 v124, v101, v17, vcc
	v_add_u32_e32 v17, 59, v82
	v_cmp_gt_u32_e32 vcc, s20, v17
	v_mul_f32_e32 v17, 0x3e38aa3b, v31
	s_nop 0
	v_cndmask_b32_e32 v125, v101, v17, vcc
	v_add_u32_e32 v17, 64, v82
	v_cmp_gt_u32_e32 vcc, s26, v18
	v_cmp_gt_u32_e64 s[6:7], s20, v17
	s_and_b64 vcc, vcc, s[6:7]
	v_add_u32_e32 v17, 0x41, v82
	s_movk_i32 s6, 0xff7e
	v_cndmask_b32_e32 v0, v101, v0, vcc
	v_cmp_lt_u32_e32 vcc, s6, v81
	v_cmp_gt_u32_e64 s[6:7], s20, v17
	s_and_b64 vcc, vcc, s[6:7]
	v_add_u32_e32 v17, 0x42, v82
	v_add_u32_e32 v18, 0x82, v81
	v_cndmask_b32_e32 v1, v101, v1, vcc
	v_cmp_gt_u32_e32 vcc, s26, v18
	v_cmp_gt_u32_e64 s[6:7], s20, v17
	s_and_b64 vcc, vcc, s[6:7]
	v_add_u32_e32 v17, 0x43, v82
	v_add_u32_e32 v18, 0x83, v81
	v_cndmask_b32_e32 v2, v101, v2, vcc
	v_cmp_gt_u32_e32 vcc, s26, v18
	v_cmp_gt_u32_e64 s[6:7], s20, v17
	s_and_b64 vcc, vcc, s[6:7]
	v_add_u32_e32 v17, 0x48, v82
	v_add_u32_e32 v18, 0x88, v81
	v_cndmask_b32_e32 v3, v101, v3, vcc
	v_cmp_gt_u32_e32 vcc, s26, v18
	v_cmp_gt_u32_e64 s[6:7], s20, v17
	s_and_b64 vcc, vcc, s[6:7]
	v_add_u32_e32 v17, 0x49, v82
	v_add_u32_e32 v18, 0x89, v81
	v_cndmask_b32_e32 v4, v101, v4, vcc
	v_cmp_gt_u32_e32 vcc, s26, v18
	v_cmp_gt_u32_e64 s[6:7], s20, v17
	s_and_b64 vcc, vcc, s[6:7]
	v_add_u32_e32 v17, 0x4a, v82
	v_add_u32_e32 v18, 0x8a, v81
	v_cndmask_b32_e32 v5, v101, v5, vcc
	v_cmp_gt_u32_e32 vcc, s26, v18
	v_cmp_gt_u32_e64 s[6:7], s20, v17
	s_and_b64 vcc, vcc, s[6:7]
	v_add_u32_e32 v17, 0x4b, v82
	v_add_u32_e32 v18, 0x8b, v81
	v_cndmask_b32_e32 v6, v101, v6, vcc
	v_cmp_gt_u32_e32 vcc, s26, v18
	v_cmp_gt_u32_e64 s[6:7], s20, v17
	s_and_b64 vcc, vcc, s[6:7]
	v_add_u32_e32 v17, 0x50, v82
	v_add_u32_e32 v18, 0x90, v81
	v_cndmask_b32_e32 v7, v101, v7, vcc
	v_cmp_gt_u32_e32 vcc, s26, v18
	v_cmp_gt_u32_e64 s[6:7], s20, v17
	s_and_b64 vcc, vcc, s[6:7]
	v_add_u32_e32 v17, 0x51, v82
	v_add_u32_e32 v18, 0x91, v81
	v_cndmask_b32_e32 v8, v101, v8, vcc
	v_cmp_gt_u32_e32 vcc, s26, v18
	v_cmp_gt_u32_e64 s[6:7], s20, v17
	s_and_b64 vcc, vcc, s[6:7]
	v_add_u32_e32 v17, 0x52, v82
	v_add_u32_e32 v18, 0x92, v81
	v_cndmask_b32_e32 v9, v101, v9, vcc
	v_cmp_gt_u32_e32 vcc, s26, v18
	v_cmp_gt_u32_e64 s[6:7], s20, v17
	s_and_b64 vcc, vcc, s[6:7]
	v_add_u32_e32 v17, 0x53, v82
	v_add_u32_e32 v18, 0x93, v81
	v_cndmask_b32_e32 v10, v101, v10, vcc
	v_cmp_gt_u32_e32 vcc, s26, v18
	v_cmp_gt_u32_e64 s[6:7], s20, v17
	s_and_b64 vcc, vcc, s[6:7]
	v_add_u32_e32 v17, 0x58, v82
	v_add_u32_e32 v18, 0x98, v81
	v_cndmask_b32_e32 v11, v101, v11, vcc
	v_cmp_gt_u32_e32 vcc, s26, v18
	v_cmp_gt_u32_e64 s[6:7], s20, v17
	v_max3_f32 v16, v16, v124, v125
	s_and_b64 vcc, vcc, s[6:7]
	v_add_u32_e32 v17, 0x59, v82
	v_add_u32_e32 v18, 0x99, v81
	v_max3_f32 v16, v16, v0, v1
	v_cndmask_b32_e32 v12, v101, v12, vcc
	v_cmp_gt_u32_e32 vcc, s26, v18
	v_cmp_gt_u32_e64 s[6:7], s20, v17
	v_max3_f32 v16, v16, v2, v3
	s_and_b64 vcc, vcc, s[6:7]
	v_add_u32_e32 v17, 0x5a, v82
	v_add_u32_e32 v18, 0x9a, v81
	v_max3_f32 v16, v16, v4, v5
	v_cndmask_b32_e32 v13, v101, v13, vcc
	v_cmp_gt_u32_e32 vcc, s26, v18
	v_cmp_gt_u32_e64 s[6:7], s20, v17
	v_max3_f32 v16, v16, v6, v7
	s_and_b64 vcc, vcc, s[6:7]
	v_add_u32_e32 v17, 0x5b, v82
	v_add_u32_e32 v18, 0x9b, v81
	v_max3_f32 v16, v16, v8, v9
	v_cndmask_b32_e32 v14, v101, v14, vcc
	v_cmp_gt_u32_e32 vcc, s26, v18
	v_cmp_gt_u32_e64 s[6:7], s20, v17
	v_max3_f32 v16, v16, v10, v11
	s_and_b64 vcc, vcc, s[6:7]
	v_max3_f32 v16, v16, v12, v13
	v_cndmask_b32_e32 v15, v101, v15, vcc
	v_lshlrev_b32_e32 v17, 2, v99
	v_max3_f32 v16, v16, v14, v15
	v_xor_b32_e32 v126, 0x80, v17
	ds_bpermute_b32 v17, v126, v16
	s_waitcnt lgkmcnt(0)
; __device__ __forceinline__ float shfl_idx(float v, int srclane) { return __int_as_float(__builtin_amdgcn_ds_bpermute(srclane << 2, __float_as_int(v))); }
; __device__ __forceinline__ void dil_wave_item(const bf16* __restrict__ qkv, bf16* __restrict__ odil, float* __restrict__ lse,
;                               int pat, int g  , int head, char* wl  , const int W) {
;     ...
;   mx = fmaxf(mx, shfl_idx(mx, lane ^ 32));
;   float ls = 0.f;
; #pragma unroll
;   for (int kb = 0; kb < 5; ++kb)
; #pragma unroll
;     for (int r = 0; r < 16; ++r) { const float e = __builtin_amdgcn_exp2f(sc[kb][r] - mx); sc[kb][r] = e; ls += e; }
;   ls += shfl_idx(ls, lane ^ 32);
	v_max_f32_e32 v17, v17, v17
	v_max_f32_e32 v34, v16, v17
	v_sub_f32_e32 v16, v64, v34
	v_exp_f32_e32 v16, v16
	v_sub_f32_e32 v17, v65, v34
	v_exp_f32_e32 v17, v17
	v_sub_f32_e32 v41, v84, v34
	v_add_f32_e32 v18, 0, v16
	v_exp_f32_e32 v41, v41
	v_add_f32_e32 v19, v17, v18
	v_sub_f32_e32 v18, v66, v34
	v_exp_f32_e32 v18, v18
	v_sub_f32_e32 v42, v50, v34
	v_exp_f32_e32 v44, v42
	v_sub_f32_e32 v42, v51, v34
	v_add_f32_e32 v20, v18, v19
	v_sub_f32_e32 v19, v83, v34
	v_exp_f32_e32 v19, v19
	v_exp_f32_e32 v50, v42
	v_sub_f32_e32 v42, v53, v34
	v_exp_f32_e32 v55, v42
	v_add_f32_e32 v21, v19, v20
	v_sub_f32_e32 v20, v67, v34
	v_exp_f32_e32 v20, v20
	v_sub_f32_e32 v42, v85, v34
	v_exp_f32_e32 v65, v42
	v_sub_f32_e32 v42, v52, v34
	v_add_f32_e32 v22, v20, v21
	v_sub_f32_e32 v21, v68, v34
	v_exp_f32_e32 v21, v21
	v_exp_f32_e32 v68, v42
	v_sub_f32_e32 v42, v54, v34
	v_sub_f32_e32 v32, v32, v34
	v_add_f32_e32 v23, v21, v22
	v_sub_f32_e32 v22, v69, v34
	v_exp_f32_e32 v22, v22
	v_sub_f32_e32 v33, v33, v34
	v_sub_f32_e32 v0, v0, v34
	v_sub_f32_e32 v1, v1, v34
	v_add_f32_e32 v24, v22, v23
	v_sub_f32_e32 v23, v71, v34
	v_exp_f32_e32 v23, v23
	s_nop 0
	v_add_f32_e32 v25, v23, v24
	v_sub_f32_e32 v24, v70, v34
	v_exp_f32_e32 v24, v24
	s_nop 0
	v_add_f32_e32 v26, v24, v25
	v_sub_f32_e32 v25, v72, v34
	v_exp_f32_e32 v25, v25
	s_nop 0
	v_add_f32_e32 v27, v25, v26
	v_sub_f32_e32 v26, v73, v34
	v_exp_f32_e32 v26, v26
	v_exp_f32_e32 v73, v42
	v_sub_f32_e32 v42, v57, v34
	v_add_f32_e32 v28, v26, v27
	v_sub_f32_e32 v27, v75, v34
	v_exp_f32_e32 v27, v27
	s_nop 0
	v_add_f32_e32 v29, v27, v28
	v_sub_f32_e32 v28, v74, v34
	v_exp_f32_e32 v28, v28
	s_nop 0
	v_add_f32_e32 v30, v28, v29
	v_sub_f32_e32 v29, v76, v34
	v_exp_f32_e32 v29, v29
	v_exp_f32_e32 v76, v42
	v_sub_f32_e32 v42, v59, v34
	v_exp_f32_e32 v81, v42
	v_add_f32_e32 v31, v29, v30
	v_sub_f32_e32 v30, v77, v34
	v_exp_f32_e32 v30, v30
	v_sub_f32_e32 v42, v56, v34
	v_exp_f32_e32 v86, v42
	v_sub_f32_e32 v42, v58, v34
	v_add_f32_e32 v37, v30, v31
	v_sub_f32_e32 v31, v78, v34
	v_exp_f32_e32 v31, v31
	v_exp_f32_e32 v89, v42
	v_sub_f32_e32 v42, v60, v34
	v_exp_f32_e32 v91, v42
	v_add_f32_e32 v38, v31, v37
	v_sub_f32_e32 v37, v48, v34
	v_exp_f32_e32 v37, v37
	v_sub_f32_e32 v42, v61, v34
	v_exp_f32_e32 v106, v42
	v_exp_f32_e32 v48, v1
	v_add_f32_e32 v39, v37, v38
	v_sub_f32_e32 v38, v49, v34
	v_exp_f32_e32 v38, v38
	v_sub_f32_e32 v1, v2, v34
	v_exp_f32_e32 v49, v1
	v_sub_f32_e32 v1, v3, v34
	v_add_f32_e32 v40, v38, v39
	v_sub_f32_e32 v39, v79, v34
	v_exp_f32_e32 v39, v39
	v_exp_f32_e32 v52, v1
	v_sub_f32_e32 v1, v4, v34
	v_exp_f32_e32 v53, v1
	v_add_f32_e32 v40, v39, v40
	v_add_f32_e32 v40, v41, v40
	v_add_f32_e32 v40, v44, v40
	v_add_f32_e32 v40, v50, v40
	v_add_f32_e32 v40, v55, v40
	v_add_f32_e32 v40, v65, v40
	v_add_f32_e32 v40, v68, v40
	v_add_f32_e32 v40, v73, v40
	v_add_f32_e32 v40, v76, v40
	v_add_f32_e32 v40, v81, v40
	v_add_f32_e32 v40, v86, v40
	v_add_f32_e32 v40, v89, v40
	v_add_f32_e32 v40, v91, v40
	v_add_f32_e32 v42, v106, v40
	v_exp_f32_e32 v40, v32
	v_sub_f32_e32 v1, v5, v34
	v_exp_f32_e32 v56, v1
	v_sub_f32_e32 v1, v6, v34
	v_add_f32_e32 v32, v40, v42
	v_exp_f32_e32 v42, v33
	v_sub_f32_e32 v33, v62, v34
	v_exp_f32_e32 v43, v33
	v_sub_f32_e32 v33, v63, v34
	v_exp_f32_e32 v47, v33
	v_sub_f32_e32 v33, v35, v34
	v_exp_f32_e32 v62, v33
	v_sub_f32_e32 v33, v36, v34
	v_add_f32_e32 v32, v42, v32
	v_exp_f32_e32 v70, v33
	v_sub_f32_e32 v33, v88, v34
	v_add_f32_e32 v32, v43, v32
	v_exp_f32_e32 v74, v33
	v_sub_f32_e32 v33, v105, v34
	v_add_f32_e32 v32, v47, v32
	v_exp_f32_e32 v77, v33
	v_sub_f32_e32 v33, v87, v34
	v_add_f32_e32 v32, v62, v32
	v_exp_f32_e32 v78, v33
	v_sub_f32_e32 v33, v90, v34
	v_add_f32_e32 v32, v70, v32
	v_exp_f32_e32 v82, v33
	v_sub_f32_e32 v33, v108, v34
	v_add_f32_e32 v32, v74, v32
	v_exp_f32_e32 v84, v33
	v_sub_f32_e32 v33, v109, v34
	v_add_f32_e32 v32, v77, v32
	v_exp_f32_e32 v88, v33
	v_sub_f32_e32 v33, v107, v34
	v_add_f32_e32 v32, v78, v32
	v_exp_f32_e32 v105, v33
	v_sub_f32_e32 v33, v45, v34
	v_add_f32_e32 v32, v82, v32
	v_exp_f32_e32 v108, v33
	v_sub_f32_e32 v33, v110, v34
	v_add_f32_e32 v32, v84, v32
	v_exp_f32_e32 v109, v33
	v_sub_f32_e32 v33, v111, v34
	v_add_f32_e32 v32, v88, v32
	v_exp_f32_e32 v111, v33
	v_sub_f32_e32 v33, v46, v34
	v_add_f32_e32 v32, v105, v32
	v_exp_f32_e32 v46, v33
	v_sub_f32_e32 v33, v104, v34
	v_add_f32_e32 v32, v108, v32
	v_exp_f32_e32 v51, v33
	v_sub_f32_e32 v33, v113, v34
	v_add_f32_e32 v32, v109, v32
	v_exp_f32_e32 v58, v33
	v_sub_f32_e32 v33, v115, v34
	v_add_f32_e32 v32, v111, v32
	v_exp_f32_e32 v67, v33
	v_sub_f32_e32 v33, v112, v34
	v_add_f32_e32 v32, v46, v32
	v_exp_f32_e32 v75, v33
	v_sub_f32_e32 v33, v114, v34
	v_add_f32_e32 v32, v51, v32
	v_exp_f32_e32 v79, v33
	v_sub_f32_e32 v33, v117, v34
	v_add_f32_e32 v32, v58, v32
	v_exp_f32_e32 v83, v33
	v_sub_f32_e32 v33, v119, v34
	v_add_f32_e32 v32, v67, v32
	v_exp_f32_e32 v85, v33
	v_sub_f32_e32 v33, v116, v34
	v_add_f32_e32 v32, v75, v32
	v_exp_f32_e32 v87, v33
	v_sub_f32_e32 v33, v118, v34
	v_add_f32_e32 v32, v79, v32
	v_exp_f32_e32 v90, v33
	v_sub_f32_e32 v33, v121, v34
	v_add_f32_e32 v32, v83, v32
	v_exp_f32_e32 v104, v33
	v_sub_f32_e32 v33, v123, v34
	v_add_f32_e32 v32, v85, v32
	v_exp_f32_e32 v107, v33
	v_sub_f32_e32 v33, v120, v34
	v_add_f32_e32 v32, v87, v32
	v_exp_f32_e32 v110, v33
	v_sub_f32_e32 v33, v122, v34
	v_add_f32_e32 v32, v90, v32
	v_exp_f32_e32 v112, v33
	v_sub_f32_e32 v33, v124, v34
	v_add_f32_e32 v32, v104, v32
	v_exp_f32_e32 v113, v33
	v_sub_f32_e32 v33, v125, v34
	v_add_f32_e32 v32, v107, v32
	v_exp_f32_e32 v114, v33
	v_add_f32_e32 v32, v110, v32
	v_exp_f32_e32 v45, v0
; __device__ __forceinline__ float shfl_idx(float v, int srclane) { return __int_as_float(__builtin_amdgcn_ds_bpermute(srclane << 2, __float_as_int(v))); }
; #define SBAR() __builtin_amdgcn_sched_barrier(0)
; __device__ __forceinline__ int v_st2(int k, int c) { const int kk = (k & ~0xC) | ((k & 4) << 1) | ((k & 8) >> 1); return ((kk >> 3) * 2 + (c >> 5)) * 512 + ((kk & 7) * 32 + (c & 31)) * 2; }
; __device__ __forceinline__ int v_rd_base(int lane) { return ((lane & 3) << 3) | (((lane >> 2) & 3) << 6) | (((lane >> 4) & 1) << 5) | (((lane >> 5) & 1) << 8); }
; __device__ __forceinline__ void dil_wave_item(const bf16* __restrict__ qkv, bf16* __restrict__ odil, float* __restrict__ lse,
;                               int pat, int g  , int head, char* wl  , const int W) {
;     ...
;     for (int r = 0; r < 16; ++r) { const float e = __builtin_amdgcn_exp2f(sc[kb][r] - mx); sc[kb][r] = e; ls += e; }
;   ls += shfl_idx(ls, lane ^ 32);
;   f32x16 o0 = {}, o1 = {};
;   const int vb = (int)(uintptr_t)wl + v_rd_base(lane);
; #pragma unroll
;   for (int kb = 0; kb < 5; ++kb) {
;     bf16x8 vr[4];
; #pragma unroll
;     for (int i = 0; i < 4; ++i) {
;       const int key = i * 8 + (lane >> 3);
;       int kc = i0 - 64 + kb * 32 + key; kc = min(max(kc, 0), L - 1);
;       vr[i] = *reinterpret_cast<const bf16x8*>(qkv + (size_t)(tbase + kc * dil) * LDQ + 2560 + head * 64 + (lane & 7) * 8);
;     }
; #pragma unroll
;     for (int i = 0; i < 4; ++i) *reinterpret_cast<bf16x8*>(wl + v_st2(i * 8 + (lane >> 3), (lane & 7) * 8)) = vr[i];
;     bf16x8 pa0, pa1;
;     PK4(sc[kb], 0, pa0); PK4(sc[kb], 8, pa1);
;     asm volatile("s_waitcnt lgkmcnt(0)" ::: "memory");
;     const s16x4 a0 = tr_read<v_rd_off2(0, 0, 0)>(vb), b0 = tr_read<v_rd_off2(0, 0, 1)>(vb), a1 = tr_read<v_rd_off2(0, 1, 0)>(vb), b1 = tr_read<v_rd_off2(0, 1, 1)>(vb);
;     const s16x4 c0 = tr_read<v_rd_off2(1, 0, 0)>(vb), d0_ = tr_read<v_rd_off2(1, 0, 1)>(vb), c1 = tr_read<v_rd_off2(1, 1, 0)>(vb), d1 = tr_read<v_rd_off2(1, 1, 1)>(vb);
;     asm volatile("s_waitcnt lgkmcnt(0)" ::: "memory"); SBAR();
;     o0 = __builtin_amdgcn_mfma_f32_32x32x16_bf16(pa0, PKV(a0, b0), o0, 0, 0, 0);
;     o0 = __builtin_amdgcn_mfma_f32_32x32x16_bf16(pa1, PKV(a1, b1), o0, 0, 0, 0);
;     o1 = __builtin_amdgcn_mfma_f32_32x32x16_bf16(pa0, PKV(c0, d0_), o1, 0, 0, 0);
;     o1 = __builtin_amdgcn_mfma_f32_32x32x16_bf16(pa1, PKV(c1, d1), o1, 0, 0, 0);
	v_add_f32_e32 v32, v112, v32
	v_add_f32_e32 v32, v113, v32
	v_add_f32_e32 v32, v114, v32
	v_add_f32_e32 v0, v45, v32
	v_add_f32_e32 v0, v48, v0
	v_add_f32_e32 v0, v49, v0
	v_exp_f32_e32 v59, v1
	v_sub_f32_e32 v1, v7, v34
	v_add_f32_e32 v0, v52, v0
	v_exp_f32_e32 v63, v1
	v_sub_f32_e32 v1, v8, v34
	v_add_f32_e32 v0, v53, v0
	v_exp_f32_e32 v54, v1
	v_sub_f32_e32 v1, v9, v34
	v_add_f32_e32 v0, v56, v0
	v_exp_f32_e32 v57, v1
	v_sub_f32_e32 v1, v10, v34
	v_add_f32_e32 v0, v59, v0
	v_exp_f32_e32 v60, v1
	v_sub_f32_e32 v1, v11, v34
	v_add_f32_e32 v0, v63, v0
	v_exp_f32_e32 v64, v1
	v_sub_f32_e32 v1, v12, v34
	v_add_f32_e32 v0, v54, v0
	v_exp_f32_e32 v66, v1
	v_sub_f32_e32 v1, v13, v34
	v_add_f32_e32 v0, v57, v0
	v_exp_f32_e32 v69, v1
	v_sub_f32_e32 v1, v14, v34
	v_add_f32_e32 v0, v60, v0
	v_exp_f32_e32 v71, v1
	v_sub_f32_e32 v1, v15, v34
	v_add_f32_e32 v0, v64, v0
	v_exp_f32_e32 v72, v1
	v_add_f32_e32 v0, v66, v0
	v_add_f32_e32 v0, v69, v0
	v_add_f32_e32 v0, v71, v0
	v_lshlrev_b32_e32 v1, 4, v103
	v_add_f32_e32 v35, v72, v0
	v_lshlrev_b32_e32 v0, 3, v99
	v_and_b32_e32 v2, 0xc0, v1
	v_lshlrev_b32_e32 v3, 1, v103
	v_and_or_b32 v2, v0, 24, v2
	v_and_b32_e32 v3, 32, v3
	v_and_b32_e32 v0, 0x100, v0
	v_bfe_u32 v116, v103, 3, 3
	v_or3_b32 v0, v2, v3, v0
	v_or_b32_e32 v12, s41, v116
	v_add_u32_e32 v61, s55, v0
	v_subrev_u32_e32 v115, 64, v12
	v_lshlrev_b32_e32 v0, 3, v103
	v_and_b32_e32 v2, 56, v0
	v_bfe_u32 v117, v0, 5, 1
	v_max_i32_e32 v0, 0, v115
	v_min_u32_e32 v0, s15, v0
	v_subrev_u32_e32 v4, 56, v12
	v_lshlrev_b32_e32 v0, s40, v0
	v_max_i32_e32 v4, 0, v4
	v_add_u32_e32 v0, s42, v0
	v_min_u32_e32 v4, s15, v4
	v_subrev_u32_e32 v8, 48, v12
	v_and_b32_e32 v118, 48, v1
	v_mad_i64_i32 v[0:1], s[6:7], v0, s24, v[96:97]
	v_lshlrev_b32_e32 v4, s40, v4
	v_max_i32_e32 v8, 0, v8
	v_lshl_add_u64 v[0:1], v[0:1], 0, s[74:75]
	v_lshlrev_b32_e32 v32, 1, v2
	v_mov_b32_e32 v33, v95
	v_add_u32_e32 v4, s42, v4
	v_min_u32_e32 v8, s15, v8
	v_subrev_u32_e32 v12, 40, v12
	v_lshl_add_u64 v[0:1], v[0:1], 0, v[32:33]
	v_mad_i64_i32 v[4:5], s[6:7], v4, s24, v[96:97]
	v_lshlrev_b32_e32 v8, s40, v8
	v_max_i32_e32 v12, 0, v12
	v_add_co_u32_e32 v0, vcc, s25, v0
	v_lshl_add_u64 v[4:5], v[4:5], 0, s[74:75]
	v_add_u32_e32 v8, s42, v8
	v_min_u32_e32 v12, s15, v12
	v_addc_co_u32_e32 v1, vcc, 0, v1, vcc
	v_lshl_add_u64 v[4:5], v[4:5], 0, v[32:33]
	v_mad_i64_i32 v[8:9], s[6:7], v8, s24, v[96:97]
	v_lshlrev_b32_e32 v12, s40, v12
	v_add_co_u32_e32 v4, vcc, s25, v4
	v_lshl_add_u64 v[8:9], v[8:9], 0, s[74:75]
	v_add_u32_e32 v12, s42, v12
	v_addc_co_u32_e32 v5, vcc, 0, v5, vcc
	v_lshl_add_u64 v[8:9], v[8:9], 0, v[32:33]
	v_mad_i64_i32 v[12:13], s[6:7], v12, s24, v[96:97]
	global_load_dwordx4 v[0:3], v[0:1], off offset:1024
	v_add_co_u32_e32 v8, vcc, s25, v8
	v_lshl_add_u64 v[12:13], v[12:13], 0, s[74:75]
	s_nop 0
	v_addc_co_u32_e32 v9, vcc, 0, v9, vcc
	v_lshl_add_u64 v[12:13], v[12:13], 0, v[32:33]
	global_load_dwordx4 v[4:7], v[4:5], off offset:1024
	v_add_co_u32_e32 v12, vcc, s25, v12
	global_load_dwordx4 v[8:11], v[8:9], off offset:1024
	s_nop 0
	v_addc_co_u32_e32 v13, vcc, 0, v13, vcc
	global_load_dwordx4 v[12:15], v[12:13], off offset:1024
	v_lshrrev_b32_e32 v103, 4, v103
	v_and_or_b32 v103, v103, 2, v117
	v_lshlrev_b32_e32 v116, 6, v116
	s_movk_i32 s6, 0xc0
	v_and_or_b32 v117, v116, s6, v118
	v_lshl_add_u32 v103, v103, 9, s55
	v_add_u32_e32 v140, v103, v117
	s_movk_i32 s6, 0x100
	ds_bpermute_b32 v36, v126, v35
	s_waitcnt vmcnt(3)
	ds_write_b128 v140, v[0:3]
	v_or3_b32 v0, v116, v118, s6
	v_add_u32_e32 v103, v103, v0
	s_waitcnt vmcnt(2)
	ds_write_b128 v103, v[4:7]
	s_waitcnt vmcnt(1)
	ds_write_b128 v140, v[8:11] offset:2048
	s_waitcnt vmcnt(0)
	ds_write_b128 v103, v[12:15] offset:2048
	v_cvt_pk_bf16_f32 v16, v16, v17
	v_cvt_pk_bf16_f32 v17, v18, v19
	v_cvt_pk_bf16_f32 v18, v20, v21
	v_cvt_pk_bf16_f32 v19, v22, v23
	v_cvt_pk_bf16_f32 v116, v24, v25
	v_cvt_pk_bf16_f32 v117, v26, v27
	v_cvt_pk_bf16_f32 v118, v28, v29
	v_cvt_pk_bf16_f32 v119, v30, v31
	s_waitcnt lgkmcnt(0)
	ds_read_b64_tr_b16 v[0:1], v61 offset:0
	ds_read_b64_tr_b16 v[2:3], v61 offset:0x400
	ds_read_b64_tr_b16 v[20:21], v61 offset:0x800
	ds_read_b64_tr_b16 v[22:23], v61 offset:0xc00
	ds_read_b64_tr_b16 v[24:25], v61 offset:0x200
	ds_read_b64_tr_b16 v[26:27], v61 offset:0x600
	ds_read_b64_tr_b16 v[120:121], v61 offset:0xa00
	ds_read_b64_tr_b16 v[122:123], v61 offset:0xe00
	s_waitcnt lgkmcnt(0)
	s_nop 0
	v_permlane32_swap_b32_e32 v16, v18
	v_permlane32_swap_b32_e32 v17, v19
	v_permlane32_swap_b32_e32 v116, v118
	v_permlane32_swap_b32_e32 v117, v119
	v_mfma_f32_32x32x16_bf16 v[0:15], v[16:19], v[0:3], 0
	s_nop 0
	v_mfma_f32_32x32x16_bf16 v[0:15], v[116:119], v[20:23], v[0:15]
	v_mfma_f32_32x32x16_bf16 v[16:31], v[16:19], v[24:27], 0
	v_mfma_f32_32x32x16_bf16 v[16:31], v[116:119], v[120:123], v[16:31]
	v_max_i32_e32 v116, 0xffffffe0, v115
	v_add_u32_e32 v116, 32, v116
	v_min_u32_e32 v116, s15, v116
	v_max_i32_e32 v118, 0xffffffd8, v115
	v_lshlrev_b32_e32 v116, s40, v116
	v_add_u32_e32 v118, 40, v118
	v_add_u32_e32 v116, s42, v116
	v_min_u32_e32 v118, s15, v118
	v_max_i32_e32 v124, 0xffffffd0, v115
	v_mad_i64_i32 v[116:117], s[6:7], v116, s24, v[96:97]
	v_lshlrev_b32_e32 v118, s40, v118
	v_add_u32_e32 v124, 48, v124
	v_lshl_add_u64 v[116:117], v[116:117], 0, s[74:75]
	v_add_u32_e32 v118, s42, v118
	v_min_u32_e32 v124, s15, v124
	v_max_i32_e32 v126, 0xffffffc8, v115
	v_lshl_add_u64 v[116:117], v[116:117], 0, v[32:33]
	v_mad_i64_i32 v[118:119], s[6:7], v118, s24, v[96:97]
	v_lshlrev_b32_e32 v124, s40, v124
	v_add_u32_e32 v126, 56, v126
	v_add_co_u32_e32 v116, vcc, s25, v116
	v_lshl_add_u64 v[118:119], v[118:119], 0, s[74:75]
	v_add_u32_e32 v124, s42, v124
	v_min_u32_e32 v126, s15, v126
	v_addc_co_u32_e32 v117, vcc, 0, v117, vcc
	v_lshl_add_u64 v[118:119], v[118:119], 0, v[32:33]
	v_mad_i64_i32 v[124:125], s[6:7], v124, s24, v[96:97]
	v_lshlrev_b32_e32 v126, s40, v126
	v_add_co_u32_e32 v120, vcc, s25, v118
	v_lshl_add_u64 v[124:125], v[124:125], 0, s[74:75]
	v_add_u32_e32 v126, s42, v126
	v_addc_co_u32_e32 v121, vcc, 0, v119, vcc
	v_lshl_add_u64 v[124:125], v[124:125], 0, v[32:33]
	v_mad_i64_i32 v[126:127], s[6:7], v126, s24, v[96:97]
	v_add_co_u32_e32 v124, vcc, s25, v124
	v_lshl_add_u64 v[126:127], v[126:127], 0, s[74:75]
	s_nop 0
	v_addc_co_u32_e32 v125, vcc, 0, v125, vcc
	v_lshl_add_u64 v[126:127], v[126:127], 0, v[32:33]
	v_add_co_u32_e32 v128, vcc, s25, v126
	global_load_dwordx4 v[116:119], v[116:117], off offset:1024
	s_nop 0
	global_load_dwordx4 v[120:123], v[120:121], off offset:1024
	v_addc_co_u32_e32 v129, vcc, 0, v127, vcc
	global_load_dwordx4 v[124:127], v[124:125], off offset:1024
	s_nop 0
	global_load_dwordx4 v[128:131], v[128:129], off offset:1024
	s_waitcnt vmcnt(3)
; #define SBAR() __builtin_amdgcn_sched_barrier(0)
; __device__ __forceinline__ int v_st2(int k, int c) { const int kk = (k & ~0xC) | ((k & 4) << 1) | ((k & 8) >> 1); return ((kk >> 3) * 2 + (c >> 5)) * 512 + ((kk & 7) * 32 + (c & 31)) * 2; }
; __device__ __forceinline__ void dil_wave_item(const bf16* __restrict__ qkv, bf16* __restrict__ odil, float* __restrict__ lse,
;                               int pat, int g  , int head, char* wl  , const int W) {
;     ...
;   for (int kb = 0; kb < 5; ++kb) {
;     bf16x8 vr[4];
; #pragma unroll
;     for (int i = 0; i < 4; ++i) {
;       const int key = i * 8 + (lane >> 3);
;       int kc = i0 - 64 + kb * 32 + key; kc = min(max(kc, 0), L - 1);
;       vr[i] = *reinterpret_cast<const bf16x8*>(qkv + (size_t)(tbase + kc * dil) * LDQ + 2560 + head * 64 + (lane & 7) * 8);
;     }
; #pragma unroll
;     for (int i = 0; i < 4; ++i) *reinterpret_cast<bf16x8*>(wl + v_st2(i * 8 + (lane >> 3), (lane & 7) * 8)) = vr[i];
;     bf16x8 pa0, pa1;
;     PK4(sc[kb], 0, pa0); PK4(sc[kb], 8, pa1);
;     asm volatile("s_waitcnt lgkmcnt(0)" ::: "memory");
;     const s16x4 a0 = tr_read<v_rd_off2(0, 0, 0)>(vb), b0 = tr_read<v_rd_off2(0, 0, 1)>(vb), a1 = tr_read<v_rd_off2(0, 1, 0)>(vb), b1 = tr_read<v_rd_off2(0, 1, 1)>(vb);
;     const s16x4 c0 = tr_read<v_rd_off2(1, 0, 0)>(vb), d0_ = tr_read<v_rd_off2(1, 0, 1)>(vb), c1 = tr_read<v_rd_off2(1, 1, 0)>(vb), d1 = tr_read<v_rd_off2(1, 1, 1)>(vb);
;     asm volatile("s_waitcnt lgkmcnt(0)" ::: "memory"); SBAR();
;     o0 = __builtin_amdgcn_mfma_f32_32x32x16_bf16(pa0, PKV(a0, b0), o0, 0, 0, 0);
;     o0 = __builtin_amdgcn_mfma_f32_32x32x16_bf16(pa1, PKV(a1, b1), o0, 0, 0, 0);
;     o1 = __builtin_amdgcn_mfma_f32_32x32x16_bf16(pa0, PKV(c0, d0_), o1, 0, 0, 0);
;     o1 = __builtin_amdgcn_mfma_f32_32x32x16_bf16(pa1, PKV(c1, d1), o1, 0, 0, 0);
	ds_write_b128 v140, v[116:119]
	s_waitcnt vmcnt(2)
	ds_write_b128 v103, v[120:123]
	s_waitcnt vmcnt(1)
	ds_write_b128 v140, v[124:127] offset:2048
	s_waitcnt vmcnt(0)
	ds_write_b128 v103, v[128:131] offset:2048
	v_cvt_pk_bf16_f32 v116, v37, v38
	v_cvt_pk_bf16_f32 v117, v39, v41
	v_cvt_pk_bf16_f32 v118, v44, v50
	v_cvt_pk_bf16_f32 v119, v55, v65
	v_cvt_pk_bf16_f32 v120, v68, v73
	v_cvt_pk_bf16_f32 v121, v76, v81
	v_cvt_pk_bf16_f32 v122, v86, v89
	v_cvt_pk_bf16_f32 v123, v91, v106
	s_waitcnt lgkmcnt(0)
	ds_read_b64_tr_b16 v[124:125], v61 offset:0
	ds_read_b64_tr_b16 v[126:127], v61 offset:0x400
	ds_read_b64_tr_b16 v[128:129], v61 offset:0x800
	ds_read_b64_tr_b16 v[130:131], v61 offset:0xc00
	ds_read_b64_tr_b16 v[132:133], v61 offset:0x200
	ds_read_b64_tr_b16 v[134:135], v61 offset:0x600
	ds_read_b64_tr_b16 v[136:137], v61 offset:0xa00
	ds_read_b64_tr_b16 v[138:139], v61 offset:0xe00
	s_waitcnt lgkmcnt(0)
	s_nop 0
	v_permlane32_swap_b32_e32 v116, v118
	v_permlane32_swap_b32_e32 v117, v119
	v_permlane32_swap_b32_e32 v120, v122
	v_permlane32_swap_b32_e32 v121, v123
	v_mfma_f32_32x32x16_bf16 v[0:15], v[116:119], v[124:127], v[0:15]
	v_mfma_f32_32x32x16_bf16 v[16:31], v[116:119], v[132:135], v[16:31]
	v_mfma_f32_32x32x16_bf16 v[0:15], v[120:123], v[128:131], v[0:15]
	v_mfma_f32_32x32x16_bf16 v[16:31], v[120:123], v[136:139], v[16:31]
	v_max_i32_e32 v37, 0xffffffc0, v115
	v_add_u32_e32 v37, 64, v37
	v_min_u32_e32 v37, s15, v37
	v_lshlrev_b32_e32 v37, s40, v37
	v_add_u32_e32 v37, s42, v37
	v_mad_i64_i32 v[38:39], s[6:7], v37, s24, v[96:97]
	v_max_i32_e32 v37, 0xffffffb8, v115
	v_add_u32_e32 v37, 0x48, v37
	v_min_u32_e32 v37, s15, v37
	v_lshlrev_b32_e32 v37, s40, v37
	v_lshl_add_u64 v[38:39], v[38:39], 0, s[74:75]
	v_add_u32_e32 v37, s42, v37
	v_lshl_add_u64 v[38:39], v[38:39], 0, v[32:33]
	v_mad_i64_i32 v[116:117], s[6:7], v37, s24, v[96:97]
	v_max_i32_e32 v37, 0xffffffb0, v115
	v_add_co_u32_e32 v38, vcc, s25, v38
	v_lshl_add_u64 v[116:117], v[116:117], 0, s[74:75]
	v_add_u32_e32 v37, 0x50, v37
	v_addc_co_u32_e32 v39, vcc, 0, v39, vcc
	v_lshl_add_u64 v[116:117], v[116:117], 0, v[32:33]
	v_min_u32_e32 v37, s15, v37
	v_add_co_u32_e32 v120, vcc, s25, v116
	v_lshlrev_b32_e32 v37, s40, v37
	s_nop 0
	v_addc_co_u32_e32 v121, vcc, 0, v117, vcc
	v_add_u32_e32 v37, s42, v37
	global_load_dwordx4 v[116:119], v[38:39], off offset:1024
	s_nop 0
	global_load_dwordx4 v[120:123], v[120:121], off offset:1024
	v_mad_i64_i32 v[38:39], s[6:7], v37, s24, v[96:97]
	v_max_i32_e32 v37, 0xffffffa8, v115
	v_add_u32_e32 v37, 0x58, v37
	v_min_u32_e32 v37, s15, v37
	v_lshlrev_b32_e32 v37, s40, v37
	v_lshl_add_u64 v[38:39], v[38:39], 0, s[74:75]
	v_add_u32_e32 v37, s42, v37
	v_lshl_add_u64 v[38:39], v[38:39], 0, v[32:33]
	v_mad_i64_i32 v[124:125], s[6:7], v37, s24, v[96:97]
	v_add_co_u32_e32 v38, vcc, s25, v38
	v_lshl_add_u64 v[124:125], v[124:125], 0, s[74:75]
	s_nop 0
	v_addc_co_u32_e32 v39, vcc, 0, v39, vcc
	v_lshl_add_u64 v[124:125], v[124:125], 0, v[32:33]
	v_add_co_u32_e32 v128, vcc, s25, v124
	s_nop 1
	v_addc_co_u32_e32 v129, vcc, 0, v125, vcc
	global_load_dwordx4 v[124:127], v[38:39], off offset:1024
	s_nop 0
	global_load_dwordx4 v[128:131], v[128:129], off offset:1024
	s_waitcnt vmcnt(3)
	ds_write_b128 v140, v[116:119]
	s_waitcnt vmcnt(2)
	ds_write_b128 v103, v[120:123]
	s_waitcnt vmcnt(1)
	ds_write_b128 v140, v[124:127] offset:2048
	s_waitcnt vmcnt(0)
	ds_write_b128 v103, v[128:131] offset:2048
	v_cvt_pk_bf16_f32 v38, v40, v42
	v_cvt_pk_bf16_f32 v39, v43, v47
	v_cvt_pk_bf16_f32 v40, v62, v70
	v_cvt_pk_bf16_f32 v41, v74, v77
	v_cvt_pk_bf16_f32 v116, v78, v82
	v_cvt_pk_bf16_f32 v117, v84, v88
	v_cvt_pk_bf16_f32 v118, v105, v108
	v_cvt_pk_bf16_f32 v119, v109, v111
	s_waitcnt lgkmcnt(0)
	ds_read_b64_tr_b16 v[120:121], v61 offset:0
	ds_read_b64_tr_b16 v[122:123], v61 offset:0x400
	ds_read_b64_tr_b16 v[124:125], v61 offset:0x800
	ds_read_b64_tr_b16 v[126:127], v61 offset:0xc00
	ds_read_b64_tr_b16 v[128:129], v61 offset:0x200
	ds_read_b64_tr_b16 v[130:131], v61 offset:0x600
	ds_read_b64_tr_b16 v[132:133], v61 offset:0xa00
	ds_read_b64_tr_b16 v[134:135], v61 offset:0xe00
	s_waitcnt lgkmcnt(0)
	s_nop 0
	v_permlane32_swap_b32_e32 v38, v40
	v_permlane32_swap_b32_e32 v39, v41
	v_permlane32_swap_b32_e32 v116, v118
	v_permlane32_swap_b32_e32 v117, v119
	v_mfma_f32_32x32x16_bf16 v[0:15], v[38:41], v[120:123], v[0:15]
	v_mfma_f32_32x32x16_bf16 v[16:31], v[38:41], v[128:131], v[16:31]
	v_mfma_f32_32x32x16_bf16 v[0:15], v[116:119], v[124:127], v[0:15]
	v_mfma_f32_32x32x16_bf16 v[16:31], v[116:119], v[132:135], v[16:31]
	v_max_i32_e32 v37, 0xffffffa0, v115
	v_add_u32_e32 v37, 0x60, v37
	v_min_u32_e32 v37, s15, v37
	v_lshlrev_b32_e32 v37, s40, v37
	v_add_u32_e32 v37, s42, v37
	v_mad_i64_i32 v[38:39], s[6:7], v37, s24, v[96:97]
	v_max_i32_e32 v37, 0xffffff98, v115
	v_add_u32_e32 v37, 0x68, v37
	v_min_u32_e32 v37, s15, v37
	v_lshlrev_b32_e32 v37, s40, v37
	v_lshl_add_u64 v[38:39], v[38:39], 0, s[74:75]
	v_add_u32_e32 v37, s42, v37
	v_lshl_add_u64 v[38:39], v[38:39], 0, v[32:33]
	v_mad_i64_i32 v[40:41], s[6:7], v37, s24, v[96:97]
	v_max_i32_e32 v37, 0xffffff90, v115
	v_add_co_u32_e32 v38, vcc, s25, v38
	v_lshl_add_u64 v[40:41], v[40:41], 0, s[74:75]
	v_add_u32_e32 v37, 0x70, v37
	v_addc_co_u32_e32 v39, vcc, 0, v39, vcc
	v_lshl_add_u64 v[40:41], v[40:41], 0, v[32:33]
	v_min_u32_e32 v37, s15, v37
	v_add_co_u32_e32 v42, vcc, s25, v40
	v_lshlrev_b32_e32 v37, s40, v37
	s_nop 0
	v_addc_co_u32_e32 v43, vcc, 0, v41, vcc
	v_add_u32_e32 v37, s42, v37
	global_load_dwordx4 v[38:41], v[38:39], off offset:1024
	s_nop 0
	global_load_dwordx4 v[116:119], v[42:43], off offset:1024
	v_mad_i64_i32 v[42:43], s[6:7], v37, s24, v[96:97]
	v_max_i32_e32 v37, 0xffffff88, v115
	v_add_u32_e32 v37, 0x78, v37
	v_min_u32_e32 v37, s15, v37
	v_lshlrev_b32_e32 v37, s40, v37
	v_lshl_add_u64 v[42:43], v[42:43], 0, s[74:75]
	v_add_u32_e32 v37, s42, v37
	v_lshl_add_u64 v[42:43], v[42:43], 0, v[32:33]
	v_mad_i64_i32 v[76:77], s[6:7], v37, s24, v[96:97]
	v_add_co_u32_e32 v42, vcc, s25, v42
	v_lshl_add_u64 v[76:77], v[76:77], 0, s[74:75]
	s_nop 0
	v_addc_co_u32_e32 v43, vcc, 0, v43, vcc
	v_lshl_add_u64 v[76:77], v[76:77], 0, v[32:33]
	v_add_co_u32_e32 v76, vcc, s25, v76
	s_nop 1
	v_addc_co_u32_e32 v77, vcc, 0, v77, vcc
	global_load_dwordx4 v[120:123], v[42:43], off offset:1024
	global_load_dwordx4 v[124:127], v[76:77], off offset:1024
	s_waitcnt vmcnt(3)
; #define SBAR() __builtin_amdgcn_sched_barrier(0)
; __device__ __forceinline__ int v_st2(int k, int c) { const int kk = (k & ~0xC) | ((k & 4) << 1) | ((k & 8) >> 1); return ((kk >> 3) * 2 + (c >> 5)) * 512 + ((kk & 7) * 32 + (c & 31)) * 2; }
; __device__ __forceinline__ void dil_wave_item(const bf16* __restrict__ qkv, bf16* __restrict__ odil, float* __restrict__ lse,
;                               int pat, int g  , int head, char* wl  , const int W) {
;     ...
;   for (int kb = 0; kb < 5; ++kb) {
;     bf16x8 vr[4];
; #pragma unroll
;     for (int i = 0; i < 4; ++i) {
;       const int key = i * 8 + (lane >> 3);
;       int kc = i0 - 64 + kb * 32 + key; kc = min(max(kc, 0), L - 1);
;       vr[i] = *reinterpret_cast<const bf16x8*>(qkv + (size_t)(tbase + kc * dil) * LDQ + 2560 + head * 64 + (lane & 7) * 8);
;     }
; #pragma unroll
;     for (int i = 0; i < 4; ++i) *reinterpret_cast<bf16x8*>(wl + v_st2(i * 8 + (lane >> 3), (lane & 7) * 8)) = vr[i];
;     bf16x8 pa0, pa1;
;     PK4(sc[kb], 0, pa0); PK4(sc[kb], 8, pa1);
;     asm volatile("s_waitcnt lgkmcnt(0)" ::: "memory");
;     const s16x4 a0 = tr_read<v_rd_off2(0, 0, 0)>(vb), b0 = tr_read<v_rd_off2(0, 0, 1)>(vb), a1 = tr_read<v_rd_off2(0, 1, 0)>(vb), b1 = tr_read<v_rd_off2(0, 1, 1)>(vb);
;     const s16x4 c0 = tr_read<v_rd_off2(1, 0, 0)>(vb), d0_ = tr_read<v_rd_off2(1, 0, 1)>(vb), c1 = tr_read<v_rd_off2(1, 1, 0)>(vb), d1 = tr_read<v_rd_off2(1, 1, 1)>(vb);
;     asm volatile("s_waitcnt lgkmcnt(0)" ::: "memory"); SBAR();
;     o0 = __builtin_amdgcn_mfma_f32_32x32x16_bf16(pa0, PKV(a0, b0), o0, 0, 0, 0);
;     o0 = __builtin_amdgcn_mfma_f32_32x32x16_bf16(pa1, PKV(a1, b1), o0, 0, 0, 0);
;     o1 = __builtin_amdgcn_mfma_f32_32x32x16_bf16(pa0, PKV(c0, d0_), o1, 0, 0, 0);
;     o1 = __builtin_amdgcn_mfma_f32_32x32x16_bf16(pa1, PKV(c1, d1), o1, 0, 0, 0);
;     SBAR();
;   }
;   if (hi == 0) lse[((size_t)pat * T + tbase + (i0 + r32) * dil) * 8 + head] = mx + __log2f(ls);
	ds_write_b128 v140, v[38:41]
	s_waitcnt vmcnt(2)
	ds_write_b128 v103, v[116:119]
	s_waitcnt vmcnt(1)
	ds_write_b128 v140, v[120:123] offset:2048
	s_waitcnt vmcnt(0)
	ds_write_b128 v103, v[124:127] offset:2048
	v_cvt_pk_bf16_f32 v38, v46, v51
	v_cvt_pk_bf16_f32 v39, v58, v67
	v_cvt_pk_bf16_f32 v40, v75, v79
	v_cvt_pk_bf16_f32 v41, v83, v85
	v_cvt_pk_bf16_f32 v74, v87, v90
	v_cvt_pk_bf16_f32 v75, v104, v107
	v_cvt_pk_bf16_f32 v76, v110, v112
	v_cvt_pk_bf16_f32 v77, v113, v114
	s_waitcnt lgkmcnt(0)
	ds_read_b64_tr_b16 v[82:83], v61 offset:0
	ds_read_b64_tr_b16 v[84:85], v61 offset:0x400
	ds_read_b64_tr_b16 v[86:87], v61 offset:0x800
	ds_read_b64_tr_b16 v[88:89], v61 offset:0xc00
	ds_read_b64_tr_b16 v[104:105], v61 offset:0x200
	ds_read_b64_tr_b16 v[106:107], v61 offset:0x600
	ds_read_b64_tr_b16 v[108:109], v61 offset:0xa00
	ds_read_b64_tr_b16 v[110:111], v61 offset:0xe00
	s_waitcnt lgkmcnt(0)
	s_nop 0
	v_permlane32_swap_b32_e32 v38, v40
	v_permlane32_swap_b32_e32 v39, v41
	v_permlane32_swap_b32_e32 v74, v76
	v_permlane32_swap_b32_e32 v75, v77
	v_mfma_f32_32x32x16_bf16 v[0:15], v[38:41], v[82:85], v[0:15]
	v_mfma_f32_32x32x16_bf16 v[16:31], v[38:41], v[104:107], v[16:31]
	v_mfma_f32_32x32x16_bf16 v[0:15], v[74:77], v[86:89], v[0:15]
	v_mfma_f32_32x32x16_bf16 v[16:31], v[74:77], v[108:111], v[16:31]
	v_max_i32_e32 v37, 0xffffff80, v115
	v_add_u32_e32 v37, 0x80, v37
	v_min_u32_e32 v37, s15, v37
	v_lshlrev_b32_e32 v37, s40, v37
	v_add_u32_e32 v37, s42, v37
	v_mad_i64_i32 v[38:39], s[6:7], v37, s24, v[96:97]
	v_max_i32_e32 v37, 0xffffff78, v115
	v_add_u32_e32 v37, 0x88, v37
	v_min_u32_e32 v37, s15, v37
	v_lshlrev_b32_e32 v37, s40, v37
	v_lshl_add_u64 v[38:39], v[38:39], 0, s[74:75]
	v_add_u32_e32 v37, s42, v37
	v_lshl_add_u64 v[38:39], v[38:39], 0, v[32:33]
	v_mad_i64_i32 v[40:41], s[6:7], v37, s24, v[96:97]
	v_max_i32_e32 v37, 0xffffff70, v115
	v_add_co_u32_e32 v38, vcc, s25, v38
	v_lshl_add_u64 v[40:41], v[40:41], 0, s[74:75]
	v_add_u32_e32 v37, 0x90, v37
	v_addc_co_u32_e32 v39, vcc, 0, v39, vcc
	v_lshl_add_u64 v[40:41], v[40:41], 0, v[32:33]
	v_min_u32_e32 v37, s15, v37
	v_add_co_u32_e32 v42, vcc, s25, v40
	v_lshlrev_b32_e32 v37, s40, v37
	s_nop 0
	v_addc_co_u32_e32 v43, vcc, 0, v41, vcc
	v_add_u32_e32 v37, s42, v37
	global_load_dwordx4 v[38:41], v[38:39], off offset:1024
	s_nop 0
	global_load_dwordx4 v[74:77], v[42:43], off offset:1024
	v_mad_i64_i32 v[42:43], s[6:7], v37, s24, v[96:97]
	v_max_i32_e32 v37, 0xffffff68, v115
	v_add_u32_e32 v37, 0x98, v37
	v_min_u32_e32 v37, s15, v37
	v_lshlrev_b32_e32 v37, s40, v37
	v_lshl_add_u64 v[42:43], v[42:43], 0, s[74:75]
	v_add_u32_e32 v37, s42, v37
	v_lshl_add_u64 v[42:43], v[42:43], 0, v[32:33]
	v_mad_i64_i32 v[46:47], s[6:7], v37, s24, v[96:97]
	v_add_co_u32_e32 v42, vcc, s25, v42
	v_lshl_add_u64 v[46:47], v[46:47], 0, s[74:75]
	s_nop 0
	v_addc_co_u32_e32 v43, vcc, 0, v43, vcc
	v_lshl_add_u64 v[32:33], v[46:47], 0, v[32:33]
	v_add_co_u32_e32 v32, vcc, s25, v32
	s_nop 1
	v_addc_co_u32_e32 v33, vcc, 0, v33, vcc
	global_load_dwordx4 v[82:85], v[42:43], off offset:1024
	global_load_dwordx4 v[86:89], v[32:33], off offset:1024
	s_waitcnt vmcnt(3)
	ds_write_b128 v140, v[38:41]
	s_waitcnt vmcnt(2)
	ds_write_b128 v103, v[74:77]
	s_waitcnt vmcnt(1)
	ds_write_b128 v140, v[82:85] offset:2048
	s_waitcnt vmcnt(0)
	ds_write_b128 v103, v[86:89] offset:2048
	v_cvt_pk_bf16_f32 v38, v45, v48
	v_cvt_pk_bf16_f32 v39, v49, v52
	v_cvt_pk_bf16_f32 v40, v53, v56
	v_cvt_pk_bf16_f32 v41, v59, v63
	v_cvt_pk_bf16_f32 v42, v54, v57
	v_cvt_pk_bf16_f32 v43, v60, v64
	v_cvt_pk_bf16_f32 v44, v66, v69
	v_cvt_pk_bf16_f32 v45, v71, v72
	s_waitcnt lgkmcnt(0)
	ds_read_b64_tr_b16 v[46:47], v61 offset:0
	ds_read_b64_tr_b16 v[48:49], v61 offset:0x400
	ds_read_b64_tr_b16 v[50:51], v61 offset:0x800
	ds_read_b64_tr_b16 v[52:53], v61 offset:0xc00
	ds_read_b64_tr_b16 v[54:55], v61 offset:0x200
	ds_read_b64_tr_b16 v[56:57], v61 offset:0x600
	ds_read_b64_tr_b16 v[62:63], v61 offset:0xa00
	ds_read_b64_tr_b16 v[64:65], v61 offset:0xe00
	s_waitcnt lgkmcnt(0)
	s_nop 0
	v_permlane32_swap_b32_e32 v38, v40
	v_permlane32_swap_b32_e32 v39, v41
	v_permlane32_swap_b32_e32 v42, v44
	v_permlane32_swap_b32_e32 v43, v45
	v_mfma_f32_32x32x16_bf16 v[0:15], v[38:41], v[46:49], v[0:15]
	v_mfma_f32_32x32x16_bf16 v[16:31], v[38:41], v[54:57], v[16:31]
	v_mfma_f32_32x32x16_bf16 v[0:15], v[42:45], v[50:53], v[0:15]
	v_mfma_f32_32x32x16_bf16 v[16:31], v[42:45], v[62:65], v[16:31]
	v_cmp_lt_u32_e32 vcc, 31, v99
	s_and_saveexec_b64 s[6:7], vcc
	s_xor_b64 s[6:7], exec, s[6:7]
	s_ashr_i32 s15, s14, 31
	s_lshl_b64 s[8:9], s[14:15], 15
	s_ashr_i32 s15, s42, 31
	s_add_u32 s20, s8, s42
	s_addc_u32 s21, s9, s15
	s_or_saveexec_b64 s[6:7], s[6:7]
	s_waitcnt lgkmcnt(14)
	v_add_f32_e32 v35, v35, v36
	v_mov_b64_e32 v[32:33], s[20:21]
	s_xor_b64 exec, exec, s[6:7]
	s_cbranch_execz .LBB0_293
	v_log_f32_e32 v32, v35
	s_ashr_i32 s15, s14, 31
	s_lshl_b64 s[8:9], s[14:15], 15
	s_ashr_i32 s14, s42, 31
	s_add_u32 s8, s8, s42
	s_addc_u32 s9, s9, s14
	v_ashrrev_i32_e32 v99, 31, v98
	v_add_f32_e32 v34, v34, v32
	v_lshl_add_u64 v[32:33], s[8:9], 0, v[98:99]
	v_lshlrev_b64 v[32:33], 5, v[32:33]
	v_lshl_add_u64 v[32:33], s[72:73], 0, v[32:33]
	global_store_dword v[32:33], v34, off
	v_mov_b64_e32 v[32:33], s[8:9]
	s_branch .LBB0_293
